# GEMM K-loops (P1/P3/P4/P5): the 20 already-satisfied s_waitcnt lgkmcnt(0) that follow 'lgkmcnt(0); s_barrier; s_setprio 1' deleted, on top of P1 LDS tables + P2 pointer SALU
# baseline (speedup 1.0000x reference)
; #define PG8_STAGE(bufoff, gbase, voff) do { _Pragma("unroll") for (int _i = 0; _i < 2; ++_i) \
;         __builtin_amdgcn_global_load_lds((const unsigned*)((const char*)(gbase) + (voff)[_i]), (PG8_LAS unsigned*)(lds + (bufoff) + ldsw + _i * 8192), 16, 0, 0); } while (0)
; #define PG8_LDA(dst, b, h) do { _Pragma("unroll") for (int m = 0; m < 4; ++m) _Pragma("unroll") for (int k = 0; k < 2; ++k) dst[m][k] = *(const PG8_LAS bf16x8*)(lds + PG8_SA(b, h) + aoff + m * 2048 + k * 1024); } while (0)
; #define PG8_LDB(dst, b, h) do { _Pragma("unroll") for (int n = 0; n < 2; ++n) _Pragma("unroll") for (int k = 0; k < 2; ++k) dst[n][k] = *(const PG8_LAS bf16x8*)(lds + PG8_SB(b, h) + boff + n * 2048 + k * 1024); } while (0)
; #define PG8_MMA(ai, bj, At, Bt) do { __builtin_amdgcn_s_setprio(1); _Pragma("unroll") for (int m = 0; m < 4; ++m) _Pragma("unroll") for (int n = 0; n < 2; ++n) _Pragma("unroll") for (int k = 0; k < 2; ++k) \
;         acc[ai][bj][m][n] = __builtin_amdgcn_mfma_f32_16x16x32_bf16(Bt[n][k], At[m][k], acc[ai][bj][m][n], 0, 0, 0); __builtin_amdgcn_s_setprio(0); } while (0)
; #define PG8_WAIT_V(n) asm volatile("s_waitcnt vmcnt(" #n ")" ::: "memory")
; #define PG8_WAIT_L(n) asm volatile("s_waitcnt lgkmcnt(" #n ")" ::: "memory")
; #define PG8_BAR __builtin_amdgcn_s_barrier()
; #define PG8_SCHED __builtin_amdgcn_sched_barrier(0)
; template <class Epi, class Sched, bool ALIGN_EPI = false, bool SP2 = false>
; __device__ __forceinline__ void gemm_phase(PG8_LAS unsigned char* lds, const Gemm g, const Sched& S, const Epi& E) {
;     ...
;             const bool last = (t == nt - 2);
;             const char* a1 = cA + (size_t)(t + 1) * kstep;
;             const char* a2 = last ? nA : cA + (size_t)(t + 2) * kstep; const char* b2 = last ? nB : cB + (size_t)(t + 2) * kstep;
;             const char* a3 = a2 + kstep; const char* b3 = b2 + kstep;
;             if (last && has_next) S.a_ready(nxt);
;             if constexpr (SP2) {
;             PG8_LDB(B0, 0, 0); PG8_LDB(B1, 0, 1); PG8_SCHED; PG8_LDA(At, 0, 0); PG8_STAGE(PG8_SA(1, 1), a1 + hstep, voffA);
;             PG8_WAIT_V(8); PG8_WAIT_L(0); PG8_BAR; PG8_MMA(0, 0, At, B0); PG8_MMA(0, 1, At, B1); PG8_BAR; PG8_SCHED;
;             PG8_LDA(At, 0, 1); PG8_STAGE(PG8_SB(0, 0), b2, voffB); PG8_STAGE(PG8_SB(0, 1), b2 + hstep, voffB); PG8_STAGE(PG8_SA(0, 0), a2, voffA);
.LBB0_246:
	ds_read_b128 v[130:133], v201
	ds_read_b128 v[134:137], v201 offset:1024
	ds_read_b128 v[176:179], v201 offset:2048
	ds_read_b128 v[180:183], v201 offset:3072
	ds_read_b128 v[184:187], v202
	ds_read_b128 v[188:191], v202 offset:1024
	ds_read_b128 v[192:195], v202 offset:2048
	ds_read_b128 v[210:213], v202 offset:3072
	s_add_u32 s0, s28, 0xfffc0080
	s_addc_u32 s1, s29, -1
	s_cmp_eq_u32 s76, 12
	s_cselect_b32 s35, s21, s1
	s_cselect_b32 s34, vcc_lo, s0
	s_cselect_b32 s31, s19, s73
	s_cselect_b32 s30, vcc_hi, s72
	v_lshl_add_u64 v[196:197], s[28:29], 0, v[170:171]
	s_add_i32 m0, s41, 0xc000
	ds_read_b128 v[214:217], v198
	ds_read_b128 v[218:221], v198 offset:1024
	ds_read_b128 v[222:225], v198 offset:2048
	ds_read_b128 v[226:229], v198 offset:3072
	ds_read_b128 v[230:233], v198 offset:4096
	ds_read_b128 v[234:237], v198 offset:5120
	ds_read_b128 v[238:241], v198 offset:6144
	ds_read_b128 v[242:245], v198 offset:7168
	global_load_lds_dwordx4 v[196:197], off
	v_lshl_add_u64 v[196:197], s[28:29], 0, v[172:173]
	s_add_i32 m0, s41, 0xe000
	s_nop 0
	global_load_lds_dwordx4 v[196:197], off
	s_waitcnt vmcnt(8)
	s_waitcnt lgkmcnt(0)
	s_barrier
	s_setprio 1
	v_mfma_f32_16x16x32_bf16 v[126:129], v[130:133], v[214:217], v[126:129]
	v_mfma_f32_16x16x32_bf16 v[122:125], v[176:179], v[214:217], v[122:125]
	v_mfma_f32_16x16x32_bf16 v[114:117], v[130:133], v[222:225], v[114:117]
	v_mfma_f32_16x16x32_bf16 v[106:109], v[176:179], v[222:225], v[106:109]
	v_mfma_f32_16x16x32_bf16 v[102:105], v[130:133], v[230:233], v[102:105]
	v_mfma_f32_16x16x32_bf16 v[94:97], v[176:179], v[230:233], v[94:97]
	v_mfma_f32_16x16x32_bf16 v[86:89], v[130:133], v[238:241], v[86:89]
	v_mfma_f32_16x16x32_bf16 v[78:81], v[176:179], v[238:241], v[78:81]
	v_mfma_f32_16x16x32_bf16 v[126:129], v[134:137], v[218:221], v[126:129]
	v_mfma_f32_16x16x32_bf16 v[122:125], v[180:183], v[218:221], v[122:125]
	v_mfma_f32_16x16x32_bf16 v[114:117], v[134:137], v[226:229], v[114:117]
	v_mfma_f32_16x16x32_bf16 v[106:109], v[180:183], v[226:229], v[106:109]
	v_mfma_f32_16x16x32_bf16 v[102:105], v[134:137], v[234:237], v[102:105]
	v_mfma_f32_16x16x32_bf16 v[94:97], v[180:183], v[234:237], v[94:97]
	v_mfma_f32_16x16x32_bf16 v[86:89], v[134:137], v[242:245], v[86:89]
	v_mfma_f32_16x16x32_bf16 v[78:81], v[180:183], v[242:245], v[78:81]
	s_setprio 0
	s_setprio 1
	v_mfma_f32_16x16x32_bf16 v[118:121], v[184:187], v[214:217], v[118:121]
	v_mfma_f32_16x16x32_bf16 v[110:113], v[192:195], v[214:217], v[110:113]
	v_mfma_f32_16x16x32_bf16 v[98:101], v[184:187], v[222:225], v[98:101]
	v_mfma_f32_16x16x32_bf16 v[90:93], v[192:195], v[222:225], v[90:93]
	v_mfma_f32_16x16x32_bf16 v[82:85], v[184:187], v[230:233], v[82:85]
	v_mfma_f32_16x16x32_bf16 v[74:77], v[192:195], v[230:233], v[74:77]
	v_mfma_f32_16x16x32_bf16 v[70:73], v[184:187], v[238:241], v[70:73]
	v_mfma_f32_16x16x32_bf16 v[66:69], v[192:195], v[238:241], v[66:69]
	v_mfma_f32_16x16x32_bf16 v[118:121], v[188:191], v[218:221], v[118:121]
	v_mfma_f32_16x16x32_bf16 v[110:113], v[210:213], v[218:221], v[110:113]
	v_mfma_f32_16x16x32_bf16 v[98:101], v[188:191], v[226:229], v[98:101]
	v_mfma_f32_16x16x32_bf16 v[90:93], v[210:213], v[226:229], v[90:93]
	v_mfma_f32_16x16x32_bf16 v[82:85], v[188:191], v[234:237], v[82:85]
	v_mfma_f32_16x16x32_bf16 v[74:77], v[210:213], v[234:237], v[74:77]
	v_mfma_f32_16x16x32_bf16 v[70:73], v[188:191], v[242:245], v[70:73]
	v_mfma_f32_16x16x32_bf16 v[66:69], v[210:213], v[242:245], v[66:69]
	s_setprio 0
	s_barrier
	s_add_i32 s0, s92, s38
	v_lshl_add_u64 v[196:197], s[30:31], 0, v[142:143]
	s_mov_b32 m0, s0
	ds_read_b128 v[214:217], v198 offset:16384
	ds_read_b128 v[218:221], v198 offset:17408
	ds_read_b128 v[222:225], v198 offset:18432
	ds_read_b128 v[226:229], v198 offset:19456
	ds_read_b128 v[230:233], v198 offset:20480
	ds_read_b128 v[234:237], v198 offset:21504
	ds_read_b128 v[238:241], v198 offset:22528
	ds_read_b128 v[242:245], v198 offset:23552
	global_load_lds_dwordx4 v[196:197], off
	s_add_i32 m0, s0, 0x2000
	s_add_u32 s0, s30, 0x40000
	v_lshl_add_u64 v[246:247], s[30:31], 0, v[138:139]
	s_addc_u32 s1, s31, 0
	s_add_i32 s77, s93, s38
	global_load_lds_dwordx4 v[246:247], off
	v_lshl_add_u64 v[248:249], s[0:1], 0, v[142:143]
	s_mov_b32 m0, s77
	v_lshl_add_u64 v[250:251], s[34:35], 0, v[140:141]
	global_load_lds_dwordx4 v[248:249], off
	v_lshl_add_u64 v[248:249], s[0:1], 0, v[138:139]
	s_add_i32 m0, s77, 0x2000
	s_nop 0
	global_load_lds_dwordx4 v[248:249], off
	v_lshl_add_u64 v[248:249], s[34:35], 0, v[144:145]
	s_mov_b32 m0, s41
	s_nop 0
	global_load_lds_dwordx4 v[248:249], off
	s_mov_b32 m0, s69
	s_nop 0
	global_load_lds_dwordx4 v[250:251], off
	s_waitcnt vmcnt(8)
	s_waitcnt lgkmcnt(0)
	s_barrier
; #define PG8_STAGE(bufoff, gbase, voff) do { _Pragma("unroll") for (int _i = 0; _i < 2; ++_i) \
;         __builtin_amdgcn_global_load_lds((const unsigned*)((const char*)(gbase) + (voff)[_i]), (PG8_LAS unsigned*)(lds + (bufoff) + ldsw + _i * 8192), 16, 0, 0); } while (0)
; #define PG8_LDA(dst, b, h) do { _Pragma("unroll") for (int m = 0; m < 4; ++m) _Pragma("unroll") for (int k = 0; k < 2; ++k) dst[m][k] = *(const PG8_LAS bf16x8*)(lds + PG8_SA(b, h) + aoff + m * 2048 + k * 1024); } while (0)
; #define PG8_LDB(dst, b, h) do { _Pragma("unroll") for (int n = 0; n < 2; ++n) _Pragma("unroll") for (int k = 0; k < 2; ++k) dst[n][k] = *(const PG8_LAS bf16x8*)(lds + PG8_SB(b, h) + boff + n * 2048 + k * 1024); } while (0)
; #define PG8_MMA(ai, bj, At, Bt) do { __builtin_amdgcn_s_setprio(1); _Pragma("unroll") for (int m = 0; m < 4; ++m) _Pragma("unroll") for (int n = 0; n < 2; ++n) _Pragma("unroll") for (int k = 0; k < 2; ++k) \
;         acc[ai][bj][m][n] = __builtin_amdgcn_mfma_f32_16x16x32_bf16(Bt[n][k], At[m][k], acc[ai][bj][m][n], 0, 0, 0); __builtin_amdgcn_s_setprio(0); } while (0)
; #define PG8_WAIT_V(n) asm volatile("s_waitcnt vmcnt(" #n ")" ::: "memory")
; #define PG8_WAIT_L(n) asm volatile("s_waitcnt lgkmcnt(" #n ")" ::: "memory")
; #define PG8_BAR __builtin_amdgcn_s_barrier()
; #define PG8_SCHED __builtin_amdgcn_sched_barrier(0)
; template <class Epi, class Sched, bool ALIGN_EPI = false, bool SP2 = false>
; __device__ __forceinline__ void gemm_phase(PG8_LAS unsigned char* lds, const Gemm g, const Sched& S, const Epi& E) {
;     ...
;             PG8_WAIT_V(8); PG8_WAIT_L(0); PG8_BAR; PG8_MMA(1, 0, At, B0); PG8_MMA(1, 1, At, B1); PG8_BAR; PG8_SCHED;
;             PG8_LDB(B0, 1, 0); PG8_LDB(B1, 1, 1); PG8_SCHED; PG8_LDA(At, 1, 0); PG8_STAGE(PG8_SA(0, 1), a2 + hstep, voffA);
;             PG8_WAIT_V(8); PG8_WAIT_L(0); PG8_BAR; PG8_MMA(0, 0, At, B0); PG8_MMA(0, 1, At, B1); PG8_BAR; PG8_SCHED;
	s_setprio 1
	v_mfma_f32_16x16x32_bf16 v[62:65], v[130:133], v[214:217], v[62:65]
	v_mfma_f32_16x16x32_bf16 v[58:61], v[176:179], v[214:217], v[58:61]
	v_mfma_f32_16x16x32_bf16 v[54:57], v[130:133], v[222:225], v[54:57]
	v_mfma_f32_16x16x32_bf16 v[46:49], v[176:179], v[222:225], v[46:49]
	v_mfma_f32_16x16x32_bf16 v[38:41], v[130:133], v[230:233], v[38:41]
	v_mfma_f32_16x16x32_bf16 v[30:33], v[176:179], v[230:233], v[30:33]
	v_mfma_f32_16x16x32_bf16 v[22:25], v[130:133], v[238:241], v[22:25]
	v_mfma_f32_16x16x32_bf16 v[14:17], v[176:179], v[238:241], v[14:17]
	v_mfma_f32_16x16x32_bf16 v[62:65], v[134:137], v[218:221], v[62:65]
	v_mfma_f32_16x16x32_bf16 v[58:61], v[180:183], v[218:221], v[58:61]
	v_mfma_f32_16x16x32_bf16 v[54:57], v[134:137], v[226:229], v[54:57]
	v_mfma_f32_16x16x32_bf16 v[46:49], v[180:183], v[226:229], v[46:49]
	v_mfma_f32_16x16x32_bf16 v[38:41], v[134:137], v[234:237], v[38:41]
	v_mfma_f32_16x16x32_bf16 v[30:33], v[180:183], v[234:237], v[30:33]
	v_mfma_f32_16x16x32_bf16 v[22:25], v[134:137], v[242:245], v[22:25]
	v_mfma_f32_16x16x32_bf16 v[14:17], v[180:183], v[242:245], v[14:17]
	s_setprio 0
	s_setprio 1
	v_mfma_f32_16x16x32_bf16 v[50:53], v[184:187], v[214:217], v[50:53]
	v_mfma_f32_16x16x32_bf16 v[42:45], v[192:195], v[214:217], v[42:45]
	v_mfma_f32_16x16x32_bf16 v[34:37], v[184:187], v[222:225], v[34:37]
	v_mfma_f32_16x16x32_bf16 v[26:29], v[192:195], v[222:225], v[26:29]
	v_mfma_f32_16x16x32_bf16 v[18:21], v[184:187], v[230:233], v[18:21]
	v_mfma_f32_16x16x32_bf16 v[10:13], v[192:195], v[230:233], v[10:13]
	v_mfma_f32_16x16x32_bf16 v[6:9], v[184:187], v[238:241], v[6:9]
	v_mfma_f32_16x16x32_bf16 v[2:5], v[192:195], v[238:241], v[2:5]
	v_mfma_f32_16x16x32_bf16 v[50:53], v[188:191], v[218:221], v[50:53]
	v_mfma_f32_16x16x32_bf16 v[42:45], v[210:213], v[218:221], v[42:45]
	v_mfma_f32_16x16x32_bf16 v[34:37], v[188:191], v[226:229], v[34:37]
	v_mfma_f32_16x16x32_bf16 v[26:29], v[210:213], v[226:229], v[26:29]
	v_mfma_f32_16x16x32_bf16 v[18:21], v[188:191], v[234:237], v[18:21]
	v_mfma_f32_16x16x32_bf16 v[10:13], v[210:213], v[234:237], v[10:13]
	v_mfma_f32_16x16x32_bf16 v[6:9], v[188:191], v[242:245], v[6:9]
	v_mfma_f32_16x16x32_bf16 v[2:5], v[210:213], v[242:245], v[2:5]
	s_setprio 0
	s_barrier
	ds_read_b128 v[130:133], v203
	ds_read_b128 v[134:137], v203 offset:1024
	ds_read_b128 v[176:179], v203 offset:2048
	ds_read_b128 v[180:183], v203 offset:3072
	ds_read_b128 v[184:187], v204
	ds_read_b128 v[188:191], v204 offset:1024
	ds_read_b128 v[192:195], v204 offset:2048
	ds_read_b128 v[210:213], v204 offset:3072
	s_add_u32 s0, s34, 0x40000
	s_addc_u32 s1, s35, 0
	s_mov_b32 m0, s82
	v_lshl_add_u64 v[252:253], s[0:1], 0, v[144:145]
	ds_read_b128 v[214:217], v198 offset:32768
	ds_read_b128 v[218:221], v198 offset:33792
	ds_read_b128 v[222:225], v198 offset:34816
	ds_read_b128 v[226:229], v198 offset:35840
	ds_read_b128 v[230:233], v198 offset:36864
	ds_read_b128 v[234:237], v198 offset:37888
	ds_read_b128 v[238:241], v198 offset:38912
	ds_read_b128 v[242:245], v198 offset:39936
	global_load_lds_dwordx4 v[252:253], off
	v_lshl_add_u64 v[252:253], s[0:1], 0, v[140:141]
	s_mov_b32 m0, s83
	s_nop 0
	global_load_lds_dwordx4 v[252:253], off
	s_waitcnt vmcnt(8)
	s_waitcnt lgkmcnt(0)
	s_barrier
	s_setprio 1
	v_mfma_f32_16x16x32_bf16 v[126:129], v[130:133], v[214:217], v[126:129]
	v_mfma_f32_16x16x32_bf16 v[122:125], v[176:179], v[214:217], v[122:125]
	v_mfma_f32_16x16x32_bf16 v[114:117], v[130:133], v[222:225], v[114:117]
	v_mfma_f32_16x16x32_bf16 v[106:109], v[176:179], v[222:225], v[106:109]
	v_mfma_f32_16x16x32_bf16 v[102:105], v[130:133], v[230:233], v[102:105]
	v_mfma_f32_16x16x32_bf16 v[94:97], v[176:179], v[230:233], v[94:97]
	v_mfma_f32_16x16x32_bf16 v[86:89], v[130:133], v[238:241], v[86:89]
	v_mfma_f32_16x16x32_bf16 v[78:81], v[176:179], v[238:241], v[78:81]
	v_mfma_f32_16x16x32_bf16 v[126:129], v[134:137], v[218:221], v[126:129]
	v_mfma_f32_16x16x32_bf16 v[122:125], v[180:183], v[218:221], v[122:125]
	v_mfma_f32_16x16x32_bf16 v[114:117], v[134:137], v[226:229], v[114:117]
	v_mfma_f32_16x16x32_bf16 v[106:109], v[180:183], v[226:229], v[106:109]
	v_mfma_f32_16x16x32_bf16 v[102:105], v[134:137], v[234:237], v[102:105]
	v_mfma_f32_16x16x32_bf16 v[94:97], v[180:183], v[234:237], v[94:97]
	v_mfma_f32_16x16x32_bf16 v[86:89], v[134:137], v[242:245], v[86:89]
	v_mfma_f32_16x16x32_bf16 v[78:81], v[180:183], v[242:245], v[78:81]
	s_setprio 0
	s_setprio 1
	v_mfma_f32_16x16x32_bf16 v[118:121], v[184:187], v[214:217], v[118:121]
	v_mfma_f32_16x16x32_bf16 v[110:113], v[192:195], v[214:217], v[110:113]
	v_mfma_f32_16x16x32_bf16 v[98:101], v[184:187], v[222:225], v[98:101]
	v_mfma_f32_16x16x32_bf16 v[90:93], v[192:195], v[222:225], v[90:93]
	v_mfma_f32_16x16x32_bf16 v[82:85], v[184:187], v[230:233], v[82:85]
	v_mfma_f32_16x16x32_bf16 v[74:77], v[192:195], v[230:233], v[74:77]
	v_mfma_f32_16x16x32_bf16 v[70:73], v[184:187], v[238:241], v[70:73]
	v_mfma_f32_16x16x32_bf16 v[66:69], v[192:195], v[238:241], v[66:69]
	v_mfma_f32_16x16x32_bf16 v[118:121], v[188:191], v[218:221], v[118:121]
	v_mfma_f32_16x16x32_bf16 v[110:113], v[210:213], v[218:221], v[110:113]
	v_mfma_f32_16x16x32_bf16 v[98:101], v[188:191], v[226:229], v[98:101]
	v_mfma_f32_16x16x32_bf16 v[90:93], v[210:213], v[226:229], v[90:93]
	v_mfma_f32_16x16x32_bf16 v[82:85], v[188:191], v[234:237], v[82:85]
	v_mfma_f32_16x16x32_bf16 v[74:77], v[210:213], v[234:237], v[74:77]
	v_mfma_f32_16x16x32_bf16 v[70:73], v[188:191], v[242:245], v[70:73]
	v_mfma_f32_16x16x32_bf16 v[66:69], v[210:213], v[242:245], v[66:69]
	s_setprio 0
	s_barrier
; #define PG8_STAGE(bufoff, gbase, voff) do { _Pragma("unroll") for (int _i = 0; _i < 2; ++_i) \
;         __builtin_amdgcn_global_load_lds((const unsigned*)((const char*)(gbase) + (voff)[_i]), (PG8_LAS unsigned*)(lds + (bufoff) + ldsw + _i * 8192), 16, 0, 0); } while (0)
; #define PG8_LDA(dst, b, h) do { _Pragma("unroll") for (int m = 0; m < 4; ++m) _Pragma("unroll") for (int k = 0; k < 2; ++k) dst[m][k] = *(const PG8_LAS bf16x8*)(lds + PG8_SA(b, h) + aoff + m * 2048 + k * 1024); } while (0)
; #define PG8_MMA(ai, bj, At, Bt) do { __builtin_amdgcn_s_setprio(1); _Pragma("unroll") for (int m = 0; m < 4; ++m) _Pragma("unroll") for (int n = 0; n < 2; ++n) _Pragma("unroll") for (int k = 0; k < 2; ++k) \
;         acc[ai][bj][m][n] = __builtin_amdgcn_mfma_f32_16x16x32_bf16(Bt[n][k], At[m][k], acc[ai][bj][m][n], 0, 0, 0); __builtin_amdgcn_s_setprio(0); } while (0)
; #define PG8_WAIT_V(n) asm volatile("s_waitcnt vmcnt(" #n ")" ::: "memory")
; #define PG8_WAIT_L(n) asm volatile("s_waitcnt lgkmcnt(" #n ")" ::: "memory")
; #define PG8_BAR __builtin_amdgcn_s_barrier()
; #define PG8_SCHED __builtin_amdgcn_sched_barrier(0)
; template <class Epi, class Sched, bool ALIGN_EPI = false, bool SP2 = false>
; __device__ __forceinline__ void gemm_phase(PG8_LAS unsigned char* lds, const Gemm g, const Sched& S, const Epi& E) {
;     ...
;             PG8_LDA(At, 1, 1); PG8_STAGE(PG8_SB(1, 0), b3, voffB); PG8_STAGE(PG8_SB(1, 1), b3 + hstep, voffB); PG8_STAGE(PG8_SA(1, 0), a3, voffA);
;             PG8_WAIT_V(8); PG8_WAIT_L(0); PG8_BAR; PG8_MMA(1, 0, At, B0); PG8_MMA(1, 1, At, B1); PG8_BAR; PG8_SCHED;
;     ...
;         if constexpr (ALIGN_EPI) { if (wr == 0) PG8_BAR; }
	s_add_i32 s0, s94, s38
	v_lshl_add_u64 v[196:197], v[196:197], 0, s[6:7]
	s_mov_b32 m0, s0
	ds_read_b128 v[214:217], v198 offset:49152
	ds_read_b128 v[218:221], v198 offset:50176
	ds_read_b128 v[222:225], v198 offset:51200
	ds_read_b128 v[226:229], v198 offset:52224
	ds_read_b128 v[230:233], v198 offset:53248
	ds_read_b128 v[234:237], v198 offset:54272
	ds_read_b128 v[238:241], v198 offset:55296
	ds_read_b128 v[242:245], v198 offset:56320
	global_load_lds_dwordx4 v[196:197], off
	s_add_i32 m0, s0, 0x2000
	s_add_u32 s0, s30, 0x40080
	v_lshl_add_u64 v[196:197], v[246:247], 0, s[6:7]
	s_addc_u32 s1, s31, 0
	s_add_i32 s30, s95, s38
	global_load_lds_dwordx4 v[196:197], off
	v_lshl_add_u64 v[196:197], s[0:1], 0, v[142:143]
	s_mov_b32 m0, s30
	s_nop 0
	global_load_lds_dwordx4 v[196:197], off
	v_lshl_add_u64 v[196:197], s[0:1], 0, v[138:139]
	s_add_i32 m0, s30, 0x2000
	s_nop 0
	global_load_lds_dwordx4 v[196:197], off
	v_lshl_add_u64 v[196:197], v[248:249], 0, s[6:7]
	s_mov_b32 m0, s85
	s_nop 0
	global_load_lds_dwordx4 v[196:197], off
	v_lshl_add_u64 v[196:197], v[250:251], 0, s[6:7]
	s_mov_b32 m0, s89
	s_nop 0
	global_load_lds_dwordx4 v[196:197], off
	s_waitcnt vmcnt(8)
	s_waitcnt lgkmcnt(0)
	s_barrier
	s_setprio 1
	v_mfma_f32_16x16x32_bf16 v[62:65], v[130:133], v[214:217], v[62:65]
	v_mfma_f32_16x16x32_bf16 v[58:61], v[176:179], v[214:217], v[58:61]
	v_mfma_f32_16x16x32_bf16 v[54:57], v[130:133], v[222:225], v[54:57]
	v_mfma_f32_16x16x32_bf16 v[46:49], v[176:179], v[222:225], v[46:49]
	v_mfma_f32_16x16x32_bf16 v[38:41], v[130:133], v[230:233], v[38:41]
	v_mfma_f32_16x16x32_bf16 v[30:33], v[176:179], v[230:233], v[30:33]
	v_mfma_f32_16x16x32_bf16 v[22:25], v[130:133], v[238:241], v[22:25]
	v_mfma_f32_16x16x32_bf16 v[14:17], v[176:179], v[238:241], v[14:17]
	v_mfma_f32_16x16x32_bf16 v[62:65], v[134:137], v[218:221], v[62:65]
	v_mfma_f32_16x16x32_bf16 v[58:61], v[180:183], v[218:221], v[58:61]
	v_mfma_f32_16x16x32_bf16 v[54:57], v[134:137], v[226:229], v[54:57]
	v_mfma_f32_16x16x32_bf16 v[46:49], v[180:183], v[226:229], v[46:49]
	v_mfma_f32_16x16x32_bf16 v[38:41], v[134:137], v[234:237], v[38:41]
	v_mfma_f32_16x16x32_bf16 v[30:33], v[180:183], v[234:237], v[30:33]
	v_mfma_f32_16x16x32_bf16 v[22:25], v[134:137], v[242:245], v[22:25]
	v_mfma_f32_16x16x32_bf16 v[14:17], v[180:183], v[242:245], v[14:17]
	s_setprio 0
	s_setprio 1
	v_mfma_f32_16x16x32_bf16 v[50:53], v[184:187], v[214:217], v[50:53]
	v_mfma_f32_16x16x32_bf16 v[42:45], v[192:195], v[214:217], v[42:45]
	v_mfma_f32_16x16x32_bf16 v[34:37], v[184:187], v[222:225], v[34:37]
	v_mfma_f32_16x16x32_bf16 v[26:29], v[192:195], v[222:225], v[26:29]
	v_mfma_f32_16x16x32_bf16 v[18:21], v[184:187], v[230:233], v[18:21]
	v_mfma_f32_16x16x32_bf16 v[10:13], v[192:195], v[230:233], v[10:13]
	v_mfma_f32_16x16x32_bf16 v[6:9], v[184:187], v[238:241], v[6:9]
	v_mfma_f32_16x16x32_bf16 v[2:5], v[192:195], v[238:241], v[2:5]
	v_mfma_f32_16x16x32_bf16 v[50:53], v[188:191], v[218:221], v[50:53]
	v_mfma_f32_16x16x32_bf16 v[42:45], v[210:213], v[218:221], v[42:45]
	v_mfma_f32_16x16x32_bf16 v[34:37], v[188:191], v[226:229], v[34:37]
	v_mfma_f32_16x16x32_bf16 v[26:29], v[210:213], v[226:229], v[26:29]
	v_mfma_f32_16x16x32_bf16 v[18:21], v[188:191], v[234:237], v[18:21]
	v_mfma_f32_16x16x32_bf16 v[10:13], v[210:213], v[234:237], v[10:13]
	v_mfma_f32_16x16x32_bf16 v[6:9], v[188:191], v[242:245], v[6:9]
	v_mfma_f32_16x16x32_bf16 v[2:5], v[210:213], v[242:245], v[2:5]
	s_setprio 0
	s_barrier
	s_add_i32 s76, s76, 2
	s_add_u32 s28, s28, 0x100
	s_addc_u32 s29, s29, 0
	s_add_u32 s72, s72, 0x100
	s_addc_u32 s73, s73, 0
	s_cmp_gt_u32 s76, 13
	s_cbranch_scc0 .LBB0_246
	s_and_b64 vcc, exec, s[8:9]
	s_cbranch_vccz .LBB0_249
	s_barrier

; #define PG8_STAGE(bufoff, gbase, voff) do { _Pragma("unroll") for (int _i = 0; _i < 2; ++_i) \
;         __builtin_amdgcn_global_load_lds((const unsigned*)((const char*)(gbase) + (voff)[_i]), (PG8_LAS unsigned*)(lds + (bufoff) + ldsw + _i * 8192), 16, 0, 0); } while (0)
; #define PG8_LDA(dst, b, h) do { _Pragma("unroll") for (int m = 0; m < 4; ++m) _Pragma("unroll") for (int k = 0; k < 2; ++k) dst[m][k] = *(const PG8_LAS bf16x8*)(lds + PG8_SA(b, h) + aoff + m * 2048 + k * 1024); } while (0)
; #define PG8_LDB(dst, b, h) do { _Pragma("unroll") for (int n = 0; n < 2; ++n) _Pragma("unroll") for (int k = 0; k < 2; ++k) dst[n][k] = *(const PG8_LAS bf16x8*)(lds + PG8_SB(b, h) + boff + n * 2048 + k * 1024); } while (0)
; #define PG8_MMA(ai, bj, At, Bt) do { __builtin_amdgcn_s_setprio(1); _Pragma("unroll") for (int m = 0; m < 4; ++m) _Pragma("unroll") for (int n = 0; n < 2; ++n) _Pragma("unroll") for (int k = 0; k < 2; ++k) \
;         acc[ai][bj][m][n] = __builtin_amdgcn_mfma_f32_16x16x32_bf16(Bt[n][k], At[m][k], acc[ai][bj][m][n], 0, 0, 0); __builtin_amdgcn_s_setprio(0); } while (0)
; #define PG8_WAIT_V(n) asm volatile("s_waitcnt vmcnt(" #n ")" ::: "memory")
; #define PG8_WAIT_L(n) asm volatile("s_waitcnt lgkmcnt(" #n ")" ::: "memory")
; #define PG8_BAR __builtin_amdgcn_s_barrier()
; #define PG8_SCHED __builtin_amdgcn_sched_barrier(0)
; template <class Epi, class Sched, bool ALIGN_EPI = false, bool SP2 = false>
; __device__ __forceinline__ void gemm_phase(PG8_LAS unsigned char* lds, const Gemm g, const Sched& S, const Epi& E) {
;     ...
;             const bool last = (t == nt - 2);
;             const char* a1 = cA + (size_t)(t + 1) * kstep;
;             const char* a2 = last ? nA : cA + (size_t)(t + 2) * kstep; const char* b2 = last ? nB : cB + (size_t)(t + 2) * kstep;
;             const char* a3 = a2 + kstep; const char* b3 = b2 + kstep;
;             if (last && has_next) S.a_ready(nxt);
;             if constexpr (SP2) {
;             PG8_LDB(B0, 0, 0); PG8_LDB(B1, 0, 1); PG8_SCHED; PG8_LDA(At, 0, 0); PG8_STAGE(PG8_SA(1, 1), a1 + hstep, voffA);
;             PG8_WAIT_V(8); PG8_WAIT_L(0); PG8_BAR; PG8_MMA(0, 0, At, B0); PG8_MMA(0, 1, At, B1); PG8_BAR; PG8_SCHED;
;             PG8_LDA(At, 0, 1); PG8_STAGE(PG8_SB(0, 0), b2, voffB); PG8_STAGE(PG8_SB(0, 1), b2 + hstep, voffB); PG8_STAGE(PG8_SA(0, 0), a2, voffA);
.LBB0_1230:
	ds_read_b128 v[144:147], v166
	ds_read_b128 v[148:151], v166 offset:1024
	ds_read_b128 v[152:155], v166 offset:2048
	ds_read_b128 v[172:175], v166 offset:3072
	ds_read_b128 v[176:179], v167
	ds_read_b128 v[180:183], v167 offset:1024
	ds_read_b128 v[184:187], v167 offset:2048
	ds_read_b128 v[188:191], v167 offset:3072
	s_add_u32 s0, s30, 0xfffc0080
	s_addc_u32 s1, s31, -1
	s_cmp_eq_u32 s76, 12
	s_cselect_b32 s37, s21, s1
	s_cselect_b32 s36, s29, s0
	s_cselect_b32 s35, s19, s73
	s_cselect_b32 s34, s84, s72
	v_lshl_add_u64 v[226:227], s[30:31], 0, v[138:139]
	s_add_i32 m0, s40, 0xc000
	ds_read_b128 v[192:195], v168
	ds_read_b128 v[196:199], v168 offset:1024
	ds_read_b128 v[200:203], v168 offset:2048
	ds_read_b128 v[204:207], v168 offset:3072
	ds_read_b128 v[210:213], v168 offset:4096
	ds_read_b128 v[214:217], v168 offset:5120
	ds_read_b128 v[218:221], v168 offset:6144
	ds_read_b128 v[222:225], v168 offset:7168
	global_load_lds_dwordx4 v[226:227], off
	v_lshl_add_u64 v[226:227], s[30:31], 0, v[140:141]
	s_add_i32 m0, s40, 0xe000
	s_nop 0
	global_load_lds_dwordx4 v[226:227], off
	s_waitcnt vmcnt(8)
	s_waitcnt lgkmcnt(0)
	s_barrier
	s_setprio 1
	v_mfma_f32_16x16x32_bf16 v[126:129], v[144:147], v[192:195], v[126:129]
	v_mfma_f32_16x16x32_bf16 v[122:125], v[152:155], v[192:195], v[122:125]
	v_mfma_f32_16x16x32_bf16 v[110:113], v[144:147], v[200:203], v[110:113]
	v_mfma_f32_16x16x32_bf16 v[106:109], v[152:155], v[200:203], v[106:109]
	v_mfma_f32_16x16x32_bf16 v[94:97], v[144:147], v[210:213], v[94:97]
	v_mfma_f32_16x16x32_bf16 v[90:93], v[152:155], v[210:213], v[90:93]
	v_mfma_f32_16x16x32_bf16 v[78:81], v[144:147], v[218:221], v[78:81]
	v_mfma_f32_16x16x32_bf16 v[74:77], v[152:155], v[218:221], v[74:77]
	v_mfma_f32_16x16x32_bf16 v[126:129], v[148:151], v[196:199], v[126:129]
	v_mfma_f32_16x16x32_bf16 v[122:125], v[172:175], v[196:199], v[122:125]
	v_mfma_f32_16x16x32_bf16 v[110:113], v[148:151], v[204:207], v[110:113]
	v_mfma_f32_16x16x32_bf16 v[106:109], v[172:175], v[204:207], v[106:109]
	v_mfma_f32_16x16x32_bf16 v[94:97], v[148:151], v[214:217], v[94:97]
	v_mfma_f32_16x16x32_bf16 v[90:93], v[172:175], v[214:217], v[90:93]
	v_mfma_f32_16x16x32_bf16 v[78:81], v[148:151], v[222:225], v[78:81]
	v_mfma_f32_16x16x32_bf16 v[74:77], v[172:175], v[222:225], v[74:77]
	s_setprio 0
	s_setprio 1
	v_mfma_f32_16x16x32_bf16 v[118:121], v[176:179], v[192:195], v[118:121]
	v_mfma_f32_16x16x32_bf16 v[114:117], v[184:187], v[192:195], v[114:117]
	v_mfma_f32_16x16x32_bf16 v[102:105], v[176:179], v[200:203], v[102:105]
	v_mfma_f32_16x16x32_bf16 v[98:101], v[184:187], v[200:203], v[98:101]
	v_mfma_f32_16x16x32_bf16 v[86:89], v[176:179], v[210:213], v[86:89]
	v_mfma_f32_16x16x32_bf16 v[82:85], v[184:187], v[210:213], v[82:85]
	v_mfma_f32_16x16x32_bf16 v[70:73], v[176:179], v[218:221], v[70:73]
	v_mfma_f32_16x16x32_bf16 v[66:69], v[184:187], v[218:221], v[66:69]
	v_mfma_f32_16x16x32_bf16 v[118:121], v[180:183], v[196:199], v[118:121]
	v_mfma_f32_16x16x32_bf16 v[114:117], v[188:191], v[196:199], v[114:117]
	v_mfma_f32_16x16x32_bf16 v[102:105], v[180:183], v[204:207], v[102:105]
	v_mfma_f32_16x16x32_bf16 v[98:101], v[188:191], v[204:207], v[98:101]
	v_mfma_f32_16x16x32_bf16 v[86:89], v[180:183], v[214:217], v[86:89]
	v_mfma_f32_16x16x32_bf16 v[82:85], v[188:191], v[214:217], v[82:85]
	v_mfma_f32_16x16x32_bf16 v[70:73], v[180:183], v[222:225], v[70:73]
	v_mfma_f32_16x16x32_bf16 v[66:69], v[188:191], v[222:225], v[66:69]
	s_setprio 0
	s_barrier
	s_add_i32 s0, s58, s39
	v_lshl_add_u64 v[226:227], s[34:35], 0, v[132:133]
	s_mov_b32 m0, s0
	ds_read_b128 v[192:195], v168 offset:16384
	ds_read_b128 v[196:199], v168 offset:17408
	ds_read_b128 v[200:203], v168 offset:18432
	ds_read_b128 v[204:207], v168 offset:19456
	ds_read_b128 v[210:213], v168 offset:20480
	ds_read_b128 v[214:217], v168 offset:21504
	ds_read_b128 v[218:221], v168 offset:22528
	ds_read_b128 v[222:225], v168 offset:23552
	global_load_lds_dwordx4 v[226:227], off
	s_add_i32 m0, s0, 0x2000
	s_add_u32 s0, s34, 0x40000
	v_lshl_add_u64 v[228:229], s[34:35], 0, v[136:137]
	s_addc_u32 s1, s35, 0
	s_add_i32 s77, s59, s39
	global_load_lds_dwordx4 v[228:229], off
	v_lshl_add_u64 v[230:231], s[0:1], 0, v[132:133]
	s_mov_b32 m0, s77
	v_lshl_add_u64 v[232:233], s[36:37], 0, v[134:135]
	global_load_lds_dwordx4 v[230:231], off
	v_lshl_add_u64 v[230:231], s[0:1], 0, v[136:137]
	s_add_i32 m0, s77, 0x2000
	s_nop 0
	global_load_lds_dwordx4 v[230:231], off
	v_lshl_add_u64 v[230:231], s[36:37], 0, v[130:131]
	s_mov_b32 m0, s40
	s_nop 0
	global_load_lds_dwordx4 v[230:231], off
	s_mov_b32 m0, s41
	s_nop 0
	global_load_lds_dwordx4 v[232:233], off
	s_waitcnt vmcnt(8)
	s_waitcnt lgkmcnt(0)
	s_barrier
; #define PG8_STAGE(bufoff, gbase, voff) do { _Pragma("unroll") for (int _i = 0; _i < 2; ++_i) \
;         __builtin_amdgcn_global_load_lds((const unsigned*)((const char*)(gbase) + (voff)[_i]), (PG8_LAS unsigned*)(lds + (bufoff) + ldsw + _i * 8192), 16, 0, 0); } while (0)
; #define PG8_LDA(dst, b, h) do { _Pragma("unroll") for (int m = 0; m < 4; ++m) _Pragma("unroll") for (int k = 0; k < 2; ++k) dst[m][k] = *(const PG8_LAS bf16x8*)(lds + PG8_SA(b, h) + aoff + m * 2048 + k * 1024); } while (0)
; #define PG8_LDB(dst, b, h) do { _Pragma("unroll") for (int n = 0; n < 2; ++n) _Pragma("unroll") for (int k = 0; k < 2; ++k) dst[n][k] = *(const PG8_LAS bf16x8*)(lds + PG8_SB(b, h) + boff + n * 2048 + k * 1024); } while (0)
; #define PG8_MMA(ai, bj, At, Bt) do { __builtin_amdgcn_s_setprio(1); _Pragma("unroll") for (int m = 0; m < 4; ++m) _Pragma("unroll") for (int n = 0; n < 2; ++n) _Pragma("unroll") for (int k = 0; k < 2; ++k) \
;         acc[ai][bj][m][n] = __builtin_amdgcn_mfma_f32_16x16x32_bf16(Bt[n][k], At[m][k], acc[ai][bj][m][n], 0, 0, 0); __builtin_amdgcn_s_setprio(0); } while (0)
; #define PG8_WAIT_V(n) asm volatile("s_waitcnt vmcnt(" #n ")" ::: "memory")
; #define PG8_WAIT_L(n) asm volatile("s_waitcnt lgkmcnt(" #n ")" ::: "memory")
; #define PG8_BAR __builtin_amdgcn_s_barrier()
; #define PG8_SCHED __builtin_amdgcn_sched_barrier(0)
; template <class Epi, class Sched, bool ALIGN_EPI = false, bool SP2 = false>
; __device__ __forceinline__ void gemm_phase(PG8_LAS unsigned char* lds, const Gemm g, const Sched& S, const Epi& E) {
;     ...
;             PG8_WAIT_V(8); PG8_WAIT_L(0); PG8_BAR; PG8_MMA(1, 0, At, B0); PG8_MMA(1, 1, At, B1); PG8_BAR; PG8_SCHED;
;             PG8_LDB(B0, 1, 0); PG8_LDB(B1, 1, 1); PG8_SCHED; PG8_LDA(At, 1, 0); PG8_STAGE(PG8_SA(0, 1), a2 + hstep, voffA);
;             PG8_WAIT_V(8); PG8_WAIT_L(0); PG8_BAR; PG8_MMA(0, 0, At, B0); PG8_MMA(0, 1, At, B1); PG8_BAR; PG8_SCHED;
	s_setprio 1
	v_mfma_f32_16x16x32_bf16 v[62:65], v[144:147], v[192:195], v[62:65]
	v_mfma_f32_16x16x32_bf16 v[58:61], v[152:155], v[192:195], v[58:61]
	v_mfma_f32_16x16x32_bf16 v[46:49], v[144:147], v[200:203], v[46:49]
	v_mfma_f32_16x16x32_bf16 v[42:45], v[152:155], v[200:203], v[42:45]
	v_mfma_f32_16x16x32_bf16 v[30:33], v[144:147], v[210:213], v[30:33]
	v_mfma_f32_16x16x32_bf16 v[26:29], v[152:155], v[210:213], v[26:29]
	v_mfma_f32_16x16x32_bf16 v[14:17], v[144:147], v[218:221], v[14:17]
	v_mfma_f32_16x16x32_bf16 v[10:13], v[152:155], v[218:221], v[10:13]
	v_mfma_f32_16x16x32_bf16 v[62:65], v[148:151], v[196:199], v[62:65]
	v_mfma_f32_16x16x32_bf16 v[58:61], v[172:175], v[196:199], v[58:61]
	v_mfma_f32_16x16x32_bf16 v[46:49], v[148:151], v[204:207], v[46:49]
	v_mfma_f32_16x16x32_bf16 v[42:45], v[172:175], v[204:207], v[42:45]
	v_mfma_f32_16x16x32_bf16 v[30:33], v[148:151], v[214:217], v[30:33]
	v_mfma_f32_16x16x32_bf16 v[26:29], v[172:175], v[214:217], v[26:29]
	v_mfma_f32_16x16x32_bf16 v[14:17], v[148:151], v[222:225], v[14:17]
	v_mfma_f32_16x16x32_bf16 v[10:13], v[172:175], v[222:225], v[10:13]
	s_setprio 0
	s_setprio 1
	v_mfma_f32_16x16x32_bf16 v[54:57], v[176:179], v[192:195], v[54:57]
	v_mfma_f32_16x16x32_bf16 v[50:53], v[184:187], v[192:195], v[50:53]
	v_mfma_f32_16x16x32_bf16 v[38:41], v[176:179], v[200:203], v[38:41]
	v_mfma_f32_16x16x32_bf16 v[34:37], v[184:187], v[200:203], v[34:37]
	v_mfma_f32_16x16x32_bf16 v[22:25], v[176:179], v[210:213], v[22:25]
	v_mfma_f32_16x16x32_bf16 v[18:21], v[184:187], v[210:213], v[18:21]
	v_mfma_f32_16x16x32_bf16 v[6:9], v[176:179], v[218:221], v[6:9]
	v_mfma_f32_16x16x32_bf16 v[2:5], v[184:187], v[218:221], v[2:5]
	v_mfma_f32_16x16x32_bf16 v[54:57], v[180:183], v[196:199], v[54:57]
	v_mfma_f32_16x16x32_bf16 v[50:53], v[188:191], v[196:199], v[50:53]
	v_mfma_f32_16x16x32_bf16 v[38:41], v[180:183], v[204:207], v[38:41]
	v_mfma_f32_16x16x32_bf16 v[34:37], v[188:191], v[204:207], v[34:37]
	v_mfma_f32_16x16x32_bf16 v[22:25], v[180:183], v[214:217], v[22:25]
	v_mfma_f32_16x16x32_bf16 v[18:21], v[188:191], v[214:217], v[18:21]
	v_mfma_f32_16x16x32_bf16 v[6:9], v[180:183], v[222:225], v[6:9]
	v_mfma_f32_16x16x32_bf16 v[2:5], v[188:191], v[222:225], v[2:5]
	s_setprio 0
	s_barrier
	ds_read_b128 v[144:147], v170
	ds_read_b128 v[148:151], v170 offset:1024
	ds_read_b128 v[152:155], v170 offset:2048
	ds_read_b128 v[172:175], v170 offset:3072
	ds_read_b128 v[176:179], v171
	ds_read_b128 v[180:183], v171 offset:1024
	ds_read_b128 v[184:187], v171 offset:2048
	ds_read_b128 v[188:191], v171 offset:3072
	s_add_u32 s0, s36, 0x40000
	s_addc_u32 s1, s37, 0
	s_mov_b32 m0, s43
	v_lshl_add_u64 v[234:235], s[0:1], 0, v[130:131]
	ds_read_b128 v[192:195], v168 offset:32768
	ds_read_b128 v[196:199], v168 offset:33792
	ds_read_b128 v[200:203], v168 offset:34816
	ds_read_b128 v[204:207], v168 offset:35840
	ds_read_b128 v[210:213], v168 offset:36864
	ds_read_b128 v[214:217], v168 offset:37888
	ds_read_b128 v[218:221], v168 offset:38912
	ds_read_b128 v[222:225], v168 offset:39936
	global_load_lds_dwordx4 v[234:235], off
	v_lshl_add_u64 v[234:235], s[0:1], 0, v[134:135]
	s_mov_b32 m0, s52
	s_nop 0
	global_load_lds_dwordx4 v[234:235], off
	s_waitcnt vmcnt(8)
	s_waitcnt lgkmcnt(0)
	s_barrier
	s_setprio 1
	v_mfma_f32_16x16x32_bf16 v[126:129], v[144:147], v[192:195], v[126:129]
	v_mfma_f32_16x16x32_bf16 v[122:125], v[152:155], v[192:195], v[122:125]
	v_mfma_f32_16x16x32_bf16 v[110:113], v[144:147], v[200:203], v[110:113]
	v_mfma_f32_16x16x32_bf16 v[106:109], v[152:155], v[200:203], v[106:109]
	v_mfma_f32_16x16x32_bf16 v[94:97], v[144:147], v[210:213], v[94:97]
	v_mfma_f32_16x16x32_bf16 v[90:93], v[152:155], v[210:213], v[90:93]
	v_mfma_f32_16x16x32_bf16 v[78:81], v[144:147], v[218:221], v[78:81]
	v_mfma_f32_16x16x32_bf16 v[74:77], v[152:155], v[218:221], v[74:77]
	v_mfma_f32_16x16x32_bf16 v[126:129], v[148:151], v[196:199], v[126:129]
	v_mfma_f32_16x16x32_bf16 v[122:125], v[172:175], v[196:199], v[122:125]
	v_mfma_f32_16x16x32_bf16 v[110:113], v[148:151], v[204:207], v[110:113]
	v_mfma_f32_16x16x32_bf16 v[106:109], v[172:175], v[204:207], v[106:109]
	v_mfma_f32_16x16x32_bf16 v[94:97], v[148:151], v[214:217], v[94:97]
	v_mfma_f32_16x16x32_bf16 v[90:93], v[172:175], v[214:217], v[90:93]
	v_mfma_f32_16x16x32_bf16 v[78:81], v[148:151], v[222:225], v[78:81]
	v_mfma_f32_16x16x32_bf16 v[74:77], v[172:175], v[222:225], v[74:77]
	s_setprio 0
	s_setprio 1
	v_mfma_f32_16x16x32_bf16 v[118:121], v[176:179], v[192:195], v[118:121]
	v_mfma_f32_16x16x32_bf16 v[114:117], v[184:187], v[192:195], v[114:117]
	v_mfma_f32_16x16x32_bf16 v[102:105], v[176:179], v[200:203], v[102:105]
	v_mfma_f32_16x16x32_bf16 v[98:101], v[184:187], v[200:203], v[98:101]
	v_mfma_f32_16x16x32_bf16 v[86:89], v[176:179], v[210:213], v[86:89]
	v_mfma_f32_16x16x32_bf16 v[82:85], v[184:187], v[210:213], v[82:85]
	v_mfma_f32_16x16x32_bf16 v[70:73], v[176:179], v[218:221], v[70:73]
	v_mfma_f32_16x16x32_bf16 v[66:69], v[184:187], v[218:221], v[66:69]
	v_mfma_f32_16x16x32_bf16 v[118:121], v[180:183], v[196:199], v[118:121]
	v_mfma_f32_16x16x32_bf16 v[114:117], v[188:191], v[196:199], v[114:117]
	v_mfma_f32_16x16x32_bf16 v[102:105], v[180:183], v[204:207], v[102:105]
	v_mfma_f32_16x16x32_bf16 v[98:101], v[188:191], v[204:207], v[98:101]
	v_mfma_f32_16x16x32_bf16 v[86:89], v[180:183], v[214:217], v[86:89]
	v_mfma_f32_16x16x32_bf16 v[82:85], v[188:191], v[214:217], v[82:85]
	v_mfma_f32_16x16x32_bf16 v[70:73], v[180:183], v[222:225], v[70:73]
	v_mfma_f32_16x16x32_bf16 v[66:69], v[188:191], v[222:225], v[66:69]
	s_setprio 0
	s_barrier
; #define PG8_STAGE(bufoff, gbase, voff) do { _Pragma("unroll") for (int _i = 0; _i < 2; ++_i) \
;         __builtin_amdgcn_global_load_lds((const unsigned*)((const char*)(gbase) + (voff)[_i]), (PG8_LAS unsigned*)(lds + (bufoff) + ldsw + _i * 8192), 16, 0, 0); } while (0)
; #define PG8_LDA(dst, b, h) do { _Pragma("unroll") for (int m = 0; m < 4; ++m) _Pragma("unroll") for (int k = 0; k < 2; ++k) dst[m][k] = *(const PG8_LAS bf16x8*)(lds + PG8_SA(b, h) + aoff + m * 2048 + k * 1024); } while (0)
; #define PG8_MMA(ai, bj, At, Bt) do { __builtin_amdgcn_s_setprio(1); _Pragma("unroll") for (int m = 0; m < 4; ++m) _Pragma("unroll") for (int n = 0; n < 2; ++n) _Pragma("unroll") for (int k = 0; k < 2; ++k) \
;         acc[ai][bj][m][n] = __builtin_amdgcn_mfma_f32_16x16x32_bf16(Bt[n][k], At[m][k], acc[ai][bj][m][n], 0, 0, 0); __builtin_amdgcn_s_setprio(0); } while (0)
; #define PG8_WAIT_V(n) asm volatile("s_waitcnt vmcnt(" #n ")" ::: "memory")
; #define PG8_WAIT_L(n) asm volatile("s_waitcnt lgkmcnt(" #n ")" ::: "memory")
; #define PG8_BAR __builtin_amdgcn_s_barrier()
; #define PG8_SCHED __builtin_amdgcn_sched_barrier(0)
; template <class Epi, class Sched, bool ALIGN_EPI = false, bool SP2 = false>
; __device__ __forceinline__ void gemm_phase(PG8_LAS unsigned char* lds, const Gemm g, const Sched& S, const Epi& E) {
;     ...
;             PG8_LDA(At, 1, 1); PG8_STAGE(PG8_SB(1, 0), b3, voffB); PG8_STAGE(PG8_SB(1, 1), b3 + hstep, voffB); PG8_STAGE(PG8_SA(1, 0), a3, voffA);
;             PG8_WAIT_V(8); PG8_WAIT_L(0); PG8_BAR; PG8_MMA(1, 0, At, B0); PG8_MMA(1, 1, At, B1); PG8_BAR; PG8_SCHED;
;     ...
;         if constexpr (ALIGN_EPI) { if (wr == 0) PG8_BAR; }
	s_add_i32 s0, s69, s39
	v_lshl_add_u64 v[226:227], v[226:227], 0, s[12:13]
	s_mov_b32 m0, s0
	ds_read_b128 v[192:195], v168 offset:49152
	ds_read_b128 v[196:199], v168 offset:50176
	ds_read_b128 v[200:203], v168 offset:51200
	ds_read_b128 v[204:207], v168 offset:52224
	ds_read_b128 v[210:213], v168 offset:53248
	ds_read_b128 v[214:217], v168 offset:54272
	ds_read_b128 v[218:221], v168 offset:55296
	ds_read_b128 v[222:225], v168 offset:56320
	global_load_lds_dwordx4 v[226:227], off
	s_add_i32 m0, s0, 0x2000
	s_add_u32 s0, s34, 0x40080
	v_lshl_add_u64 v[226:227], v[228:229], 0, s[12:13]
	s_addc_u32 s1, s35, 0
	s_add_i32 s34, s82, s39
	global_load_lds_dwordx4 v[226:227], off
	v_lshl_add_u64 v[226:227], s[0:1], 0, v[132:133]
	s_mov_b32 m0, s34
	s_nop 0
	global_load_lds_dwordx4 v[226:227], off
	v_lshl_add_u64 v[226:227], s[0:1], 0, v[136:137]
	s_add_i32 m0, s34, 0x2000
	s_nop 0
	global_load_lds_dwordx4 v[226:227], off
	v_lshl_add_u64 v[226:227], v[230:231], 0, s[12:13]
	s_mov_b32 m0, s54
	s_nop 0
	global_load_lds_dwordx4 v[226:227], off
	v_lshl_add_u64 v[226:227], v[232:233], 0, s[12:13]
	s_mov_b32 m0, s55
	s_nop 0
	global_load_lds_dwordx4 v[226:227], off
	s_waitcnt vmcnt(8)
	s_waitcnt lgkmcnt(0)
	s_barrier
	s_setprio 1
	v_mfma_f32_16x16x32_bf16 v[62:65], v[144:147], v[192:195], v[62:65]
	v_mfma_f32_16x16x32_bf16 v[58:61], v[152:155], v[192:195], v[58:61]
	v_mfma_f32_16x16x32_bf16 v[46:49], v[144:147], v[200:203], v[46:49]
	v_mfma_f32_16x16x32_bf16 v[42:45], v[152:155], v[200:203], v[42:45]
	v_mfma_f32_16x16x32_bf16 v[30:33], v[144:147], v[210:213], v[30:33]
	v_mfma_f32_16x16x32_bf16 v[26:29], v[152:155], v[210:213], v[26:29]
	v_mfma_f32_16x16x32_bf16 v[14:17], v[144:147], v[218:221], v[14:17]
	v_mfma_f32_16x16x32_bf16 v[10:13], v[152:155], v[218:221], v[10:13]
	v_mfma_f32_16x16x32_bf16 v[62:65], v[148:151], v[196:199], v[62:65]
	v_mfma_f32_16x16x32_bf16 v[58:61], v[172:175], v[196:199], v[58:61]
	v_mfma_f32_16x16x32_bf16 v[46:49], v[148:151], v[204:207], v[46:49]
	v_mfma_f32_16x16x32_bf16 v[42:45], v[172:175], v[204:207], v[42:45]
	v_mfma_f32_16x16x32_bf16 v[30:33], v[148:151], v[214:217], v[30:33]
	v_mfma_f32_16x16x32_bf16 v[26:29], v[172:175], v[214:217], v[26:29]
	v_mfma_f32_16x16x32_bf16 v[14:17], v[148:151], v[222:225], v[14:17]
	v_mfma_f32_16x16x32_bf16 v[10:13], v[172:175], v[222:225], v[10:13]
	s_setprio 0
	s_setprio 1
	v_mfma_f32_16x16x32_bf16 v[54:57], v[176:179], v[192:195], v[54:57]
	v_mfma_f32_16x16x32_bf16 v[50:53], v[184:187], v[192:195], v[50:53]
	v_mfma_f32_16x16x32_bf16 v[38:41], v[176:179], v[200:203], v[38:41]
	v_mfma_f32_16x16x32_bf16 v[34:37], v[184:187], v[200:203], v[34:37]
	v_mfma_f32_16x16x32_bf16 v[22:25], v[176:179], v[210:213], v[22:25]
	v_mfma_f32_16x16x32_bf16 v[18:21], v[184:187], v[210:213], v[18:21]
	v_mfma_f32_16x16x32_bf16 v[6:9], v[176:179], v[218:221], v[6:9]
	v_mfma_f32_16x16x32_bf16 v[2:5], v[184:187], v[218:221], v[2:5]
	v_mfma_f32_16x16x32_bf16 v[54:57], v[180:183], v[196:199], v[54:57]
	v_mfma_f32_16x16x32_bf16 v[50:53], v[188:191], v[196:199], v[50:53]
	v_mfma_f32_16x16x32_bf16 v[38:41], v[180:183], v[204:207], v[38:41]
	v_mfma_f32_16x16x32_bf16 v[34:37], v[188:191], v[204:207], v[34:37]
	v_mfma_f32_16x16x32_bf16 v[22:25], v[180:183], v[214:217], v[22:25]
	v_mfma_f32_16x16x32_bf16 v[18:21], v[188:191], v[214:217], v[18:21]
	v_mfma_f32_16x16x32_bf16 v[6:9], v[180:183], v[222:225], v[6:9]
	v_mfma_f32_16x16x32_bf16 v[2:5], v[188:191], v[222:225], v[2:5]
	s_setprio 0
	s_barrier
	s_add_i32 s76, s76, 2
	s_add_u32 s30, s30, 0x100
	s_addc_u32 s31, s31, 0
	s_add_u32 s72, s72, 0x100
	s_addc_u32 s73, s73, 0
	s_cmp_gt_u32 s76, 13
	s_cbranch_scc0 .LBB0_1230
	s_and_b64 vcc, exec, s[14:15]
	s_cbranch_vccz .LBB0_1233
	s_barrier

; #define PG8_STAGE(bufoff, gbase, voff) do { _Pragma("unroll") for (int _i = 0; _i < 2; ++_i) \
;         __builtin_amdgcn_global_load_lds((const unsigned*)((const char*)(gbase) + (voff)[_i]), (PG8_LAS unsigned*)(lds + (bufoff) + ldsw + _i * 8192), 16, 0, 0); } while (0)
; #define PG8_LDA(dst, b, h) do { _Pragma("unroll") for (int m = 0; m < 4; ++m) _Pragma("unroll") for (int k = 0; k < 2; ++k) dst[m][k] = *(const PG8_LAS bf16x8*)(lds + PG8_SA(b, h) + aoff + m * 2048 + k * 1024); } while (0)
; #define PG8_LDB(dst, b, h) do { _Pragma("unroll") for (int n = 0; n < 2; ++n) _Pragma("unroll") for (int k = 0; k < 2; ++k) dst[n][k] = *(const PG8_LAS bf16x8*)(lds + PG8_SB(b, h) + boff + n * 2048 + k * 1024); } while (0)
; #define PG8_MMA(ai, bj, At, Bt) do { __builtin_amdgcn_s_setprio(1); _Pragma("unroll") for (int m = 0; m < 4; ++m) _Pragma("unroll") for (int n = 0; n < 2; ++n) _Pragma("unroll") for (int k = 0; k < 2; ++k) \
;         acc[ai][bj][m][n] = __builtin_amdgcn_mfma_f32_16x16x32_bf16(Bt[n][k], At[m][k], acc[ai][bj][m][n], 0, 0, 0); __builtin_amdgcn_s_setprio(0); } while (0)
; #define PG8_WAIT_V(n) asm volatile("s_waitcnt vmcnt(" #n ")" ::: "memory")
; #define PG8_WAIT_L(n) asm volatile("s_waitcnt lgkmcnt(" #n ")" ::: "memory")
; #define PG8_BAR __builtin_amdgcn_s_barrier()
; #define PG8_SCHED __builtin_amdgcn_sched_barrier(0)
; template <class Epi, class Sched, bool ALIGN_EPI = false, bool SP2 = false>
; __device__ __forceinline__ void gemm_phase(PG8_LAS unsigned char* lds, const Gemm g, const Sched& S, const Epi& E) {
;     ...
;             const bool last = (t == nt - 2);
;             const char* a1 = cA + (size_t)(t + 1) * kstep;
;             const char* a2 = last ? nA : cA + (size_t)(t + 2) * kstep; const char* b2 = last ? nB : cB + (size_t)(t + 2) * kstep;
;             const char* a3 = a2 + kstep; const char* b3 = b2 + kstep;
;             if (last && has_next) S.a_ready(nxt);
;             if constexpr (SP2) {
;             PG8_LDB(B0, 0, 0); PG8_LDB(B1, 0, 1); PG8_SCHED; PG8_LDA(At, 0, 0); PG8_STAGE(PG8_SA(1, 1), a1 + hstep, voffA);
;             PG8_WAIT_V(8); PG8_WAIT_L(0); PG8_BAR; PG8_MMA(0, 0, At, B0); PG8_MMA(0, 1, At, B1); PG8_BAR; PG8_SCHED;
;             PG8_LDA(At, 0, 1); PG8_STAGE(PG8_SB(0, 0), b2, voffB); PG8_STAGE(PG8_SB(0, 1), b2 + hstep, voffB); PG8_STAGE(PG8_SA(0, 0), a2, voffA);
.LBB0_1267:
	ds_read_b128 v[144:147], v1
	ds_read_b128 v[156:159], v1 offset:1024
	ds_read_b128 v[160:163], v1 offset:2048
	ds_read_b128 v[164:167], v1 offset:3072
	ds_read_b128 v[168:171], v150
	ds_read_b128 v[172:175], v150 offset:1024
	ds_read_b128 v[176:179], v150 offset:2048
	ds_read_b128 v[180:183], v150 offset:3072
	s_add_u32 s0, s28, 0xfffc0080
	s_addc_u32 s1, s29, -1
	s_cmp_eq_u32 s73, 12
	s_cselect_b32 s35, s19, s1
	s_cselect_b32 s34, s27, s0
	s_cselect_b32 s31, s17, s72
	s_cselect_b32 s30, s59, s69
	v_lshl_add_u64 v[218:219], s[28:29], 0, v[138:139]
	s_add_i32 m0, s37, 0xc000
	ds_read_b128 v[184:187], v151
	ds_read_b128 v[188:191], v151 offset:1024
	ds_read_b128 v[192:195], v151 offset:2048
	ds_read_b128 v[196:199], v151 offset:3072
	ds_read_b128 v[200:203], v151 offset:4096
	ds_read_b128 v[204:207], v151 offset:5120
	ds_read_b128 v[210:213], v151 offset:6144
	ds_read_b128 v[214:217], v151 offset:7168
	global_load_lds_dwordx4 v[218:219], off
	v_lshl_add_u64 v[218:219], s[28:29], 0, v[140:141]
	s_add_i32 m0, s37, 0xe000
	s_nop 0
	global_load_lds_dwordx4 v[218:219], off
	s_waitcnt vmcnt(8)
	s_waitcnt lgkmcnt(0)
	s_barrier
	s_setprio 1
	v_mfma_f32_16x16x32_bf16 v[126:129], v[144:147], v[184:187], v[126:129]
	v_mfma_f32_16x16x32_bf16 v[122:125], v[160:163], v[184:187], v[122:125]
	v_mfma_f32_16x16x32_bf16 v[110:113], v[144:147], v[192:195], v[110:113]
	v_mfma_f32_16x16x32_bf16 v[106:109], v[160:163], v[192:195], v[106:109]
	v_mfma_f32_16x16x32_bf16 v[94:97], v[144:147], v[200:203], v[94:97]
	v_mfma_f32_16x16x32_bf16 v[90:93], v[160:163], v[200:203], v[90:93]
	v_mfma_f32_16x16x32_bf16 v[78:81], v[144:147], v[210:213], v[78:81]
	v_mfma_f32_16x16x32_bf16 v[74:77], v[160:163], v[210:213], v[74:77]
	v_mfma_f32_16x16x32_bf16 v[126:129], v[156:159], v[188:191], v[126:129]
	v_mfma_f32_16x16x32_bf16 v[122:125], v[164:167], v[188:191], v[122:125]
	v_mfma_f32_16x16x32_bf16 v[110:113], v[156:159], v[196:199], v[110:113]
	v_mfma_f32_16x16x32_bf16 v[106:109], v[164:167], v[196:199], v[106:109]
	v_mfma_f32_16x16x32_bf16 v[94:97], v[156:159], v[204:207], v[94:97]
	v_mfma_f32_16x16x32_bf16 v[90:93], v[164:167], v[204:207], v[90:93]
	v_mfma_f32_16x16x32_bf16 v[78:81], v[156:159], v[214:217], v[78:81]
	v_mfma_f32_16x16x32_bf16 v[74:77], v[164:167], v[214:217], v[74:77]
	s_setprio 0
	s_setprio 1
	v_mfma_f32_16x16x32_bf16 v[118:121], v[168:171], v[184:187], v[118:121]
	v_mfma_f32_16x16x32_bf16 v[114:117], v[176:179], v[184:187], v[114:117]
	v_mfma_f32_16x16x32_bf16 v[102:105], v[168:171], v[192:195], v[102:105]
	v_mfma_f32_16x16x32_bf16 v[98:101], v[176:179], v[192:195], v[98:101]
	v_mfma_f32_16x16x32_bf16 v[86:89], v[168:171], v[200:203], v[86:89]
	v_mfma_f32_16x16x32_bf16 v[82:85], v[176:179], v[200:203], v[82:85]
	v_mfma_f32_16x16x32_bf16 v[70:73], v[168:171], v[210:213], v[70:73]
	v_mfma_f32_16x16x32_bf16 v[66:69], v[176:179], v[210:213], v[66:69]
	v_mfma_f32_16x16x32_bf16 v[118:121], v[172:175], v[188:191], v[118:121]
	v_mfma_f32_16x16x32_bf16 v[114:117], v[180:183], v[188:191], v[114:117]
	v_mfma_f32_16x16x32_bf16 v[102:105], v[172:175], v[196:199], v[102:105]
	v_mfma_f32_16x16x32_bf16 v[98:101], v[180:183], v[196:199], v[98:101]
	v_mfma_f32_16x16x32_bf16 v[86:89], v[172:175], v[204:207], v[86:89]
	v_mfma_f32_16x16x32_bf16 v[82:85], v[180:183], v[204:207], v[82:85]
	v_mfma_f32_16x16x32_bf16 v[70:73], v[172:175], v[214:217], v[70:73]
	v_mfma_f32_16x16x32_bf16 v[66:69], v[180:183], v[214:217], v[66:69]
	s_setprio 0
	s_barrier
	s_add_i32 s0, s54, s36
	v_lshl_add_u64 v[218:219], s[30:31], 0, v[132:133]
	s_mov_b32 m0, s0
	ds_read_b128 v[184:187], v151 offset:16384
	ds_read_b128 v[188:191], v151 offset:17408
	ds_read_b128 v[192:195], v151 offset:18432
	ds_read_b128 v[196:199], v151 offset:19456
	ds_read_b128 v[200:203], v151 offset:20480
	ds_read_b128 v[204:207], v151 offset:21504
	ds_read_b128 v[210:213], v151 offset:22528
	ds_read_b128 v[214:217], v151 offset:23552
	global_load_lds_dwordx4 v[218:219], off
	s_add_i32 m0, s0, 0x2000
	s_add_u32 s0, s30, 0x40000
	v_lshl_add_u64 v[220:221], s[30:31], 0, v[136:137]
	s_addc_u32 s1, s31, 0
	s_add_i32 s76, s55, s36
	global_load_lds_dwordx4 v[220:221], off
	v_lshl_add_u64 v[222:223], s[0:1], 0, v[132:133]
	s_mov_b32 m0, s76
	v_lshl_add_u64 v[224:225], s[34:35], 0, v[134:135]
	global_load_lds_dwordx4 v[222:223], off
	v_lshl_add_u64 v[222:223], s[0:1], 0, v[136:137]
	s_add_i32 m0, s76, 0x2000
	s_nop 0
	global_load_lds_dwordx4 v[222:223], off
	v_lshl_add_u64 v[222:223], s[34:35], 0, v[130:131]
	s_mov_b32 m0, s37
	s_nop 0
	global_load_lds_dwordx4 v[222:223], off
	s_mov_b32 m0, s39
	s_nop 0
	global_load_lds_dwordx4 v[224:225], off
	s_waitcnt vmcnt(8)
	s_waitcnt lgkmcnt(0)
	s_barrier
; #define PG8_STAGE(bufoff, gbase, voff) do { _Pragma("unroll") for (int _i = 0; _i < 2; ++_i) \
;         __builtin_amdgcn_global_load_lds((const unsigned*)((const char*)(gbase) + (voff)[_i]), (PG8_LAS unsigned*)(lds + (bufoff) + ldsw + _i * 8192), 16, 0, 0); } while (0)
; #define PG8_LDA(dst, b, h) do { _Pragma("unroll") for (int m = 0; m < 4; ++m) _Pragma("unroll") for (int k = 0; k < 2; ++k) dst[m][k] = *(const PG8_LAS bf16x8*)(lds + PG8_SA(b, h) + aoff + m * 2048 + k * 1024); } while (0)
; #define PG8_LDB(dst, b, h) do { _Pragma("unroll") for (int n = 0; n < 2; ++n) _Pragma("unroll") for (int k = 0; k < 2; ++k) dst[n][k] = *(const PG8_LAS bf16x8*)(lds + PG8_SB(b, h) + boff + n * 2048 + k * 1024); } while (0)
; #define PG8_MMA(ai, bj, At, Bt) do { __builtin_amdgcn_s_setprio(1); _Pragma("unroll") for (int m = 0; m < 4; ++m) _Pragma("unroll") for (int n = 0; n < 2; ++n) _Pragma("unroll") for (int k = 0; k < 2; ++k) \
;         acc[ai][bj][m][n] = __builtin_amdgcn_mfma_f32_16x16x32_bf16(Bt[n][k], At[m][k], acc[ai][bj][m][n], 0, 0, 0); __builtin_amdgcn_s_setprio(0); } while (0)
; #define PG8_WAIT_V(n) asm volatile("s_waitcnt vmcnt(" #n ")" ::: "memory")
; #define PG8_WAIT_L(n) asm volatile("s_waitcnt lgkmcnt(" #n ")" ::: "memory")
; #define PG8_BAR __builtin_amdgcn_s_barrier()
; #define PG8_SCHED __builtin_amdgcn_sched_barrier(0)
; template <class Epi, class Sched, bool ALIGN_EPI = false, bool SP2 = false>
; __device__ __forceinline__ void gemm_phase(PG8_LAS unsigned char* lds, const Gemm g, const Sched& S, const Epi& E) {
;     ...
;             PG8_WAIT_V(8); PG8_WAIT_L(0); PG8_BAR; PG8_MMA(1, 0, At, B0); PG8_MMA(1, 1, At, B1); PG8_BAR; PG8_SCHED;
;             PG8_LDB(B0, 1, 0); PG8_LDB(B1, 1, 1); PG8_SCHED; PG8_LDA(At, 1, 0); PG8_STAGE(PG8_SA(0, 1), a2 + hstep, voffA);
;             PG8_WAIT_V(8); PG8_WAIT_L(0); PG8_BAR; PG8_MMA(0, 0, At, B0); PG8_MMA(0, 1, At, B1); PG8_BAR; PG8_SCHED;
	s_setprio 1
	v_mfma_f32_16x16x32_bf16 v[62:65], v[144:147], v[184:187], v[62:65]
	v_mfma_f32_16x16x32_bf16 v[58:61], v[160:163], v[184:187], v[58:61]
	v_mfma_f32_16x16x32_bf16 v[46:49], v[144:147], v[192:195], v[46:49]
	v_mfma_f32_16x16x32_bf16 v[42:45], v[160:163], v[192:195], v[42:45]
	v_mfma_f32_16x16x32_bf16 v[30:33], v[144:147], v[200:203], v[30:33]
	v_mfma_f32_16x16x32_bf16 v[26:29], v[160:163], v[200:203], v[26:29]
	v_mfma_f32_16x16x32_bf16 v[14:17], v[144:147], v[210:213], v[14:17]
	v_mfma_f32_16x16x32_bf16 v[10:13], v[160:163], v[210:213], v[10:13]
	v_mfma_f32_16x16x32_bf16 v[62:65], v[156:159], v[188:191], v[62:65]
	v_mfma_f32_16x16x32_bf16 v[58:61], v[164:167], v[188:191], v[58:61]
	v_mfma_f32_16x16x32_bf16 v[46:49], v[156:159], v[196:199], v[46:49]
	v_mfma_f32_16x16x32_bf16 v[42:45], v[164:167], v[196:199], v[42:45]
	v_mfma_f32_16x16x32_bf16 v[30:33], v[156:159], v[204:207], v[30:33]
	v_mfma_f32_16x16x32_bf16 v[26:29], v[164:167], v[204:207], v[26:29]
	v_mfma_f32_16x16x32_bf16 v[14:17], v[156:159], v[214:217], v[14:17]
	v_mfma_f32_16x16x32_bf16 v[10:13], v[164:167], v[214:217], v[10:13]
	s_setprio 0
	s_setprio 1
	v_mfma_f32_16x16x32_bf16 v[54:57], v[168:171], v[184:187], v[54:57]
	v_mfma_f32_16x16x32_bf16 v[50:53], v[176:179], v[184:187], v[50:53]
	v_mfma_f32_16x16x32_bf16 v[38:41], v[168:171], v[192:195], v[38:41]
	v_mfma_f32_16x16x32_bf16 v[34:37], v[176:179], v[192:195], v[34:37]
	v_mfma_f32_16x16x32_bf16 v[22:25], v[168:171], v[200:203], v[22:25]
	v_mfma_f32_16x16x32_bf16 v[18:21], v[176:179], v[200:203], v[18:21]
	v_mfma_f32_16x16x32_bf16 v[6:9], v[168:171], v[210:213], v[6:9]
	v_mfma_f32_16x16x32_bf16 v[2:5], v[176:179], v[210:213], v[2:5]
	v_mfma_f32_16x16x32_bf16 v[54:57], v[172:175], v[188:191], v[54:57]
	v_mfma_f32_16x16x32_bf16 v[50:53], v[180:183], v[188:191], v[50:53]
	v_mfma_f32_16x16x32_bf16 v[38:41], v[172:175], v[196:199], v[38:41]
	v_mfma_f32_16x16x32_bf16 v[34:37], v[180:183], v[196:199], v[34:37]
	v_mfma_f32_16x16x32_bf16 v[22:25], v[172:175], v[204:207], v[22:25]
	v_mfma_f32_16x16x32_bf16 v[18:21], v[180:183], v[204:207], v[18:21]
	v_mfma_f32_16x16x32_bf16 v[6:9], v[172:175], v[214:217], v[6:9]
	v_mfma_f32_16x16x32_bf16 v[2:5], v[180:183], v[214:217], v[2:5]
	s_setprio 0
	s_barrier
	ds_read_b128 v[144:147], v153
	ds_read_b128 v[156:159], v153 offset:1024
	ds_read_b128 v[160:163], v153 offset:2048
	ds_read_b128 v[164:167], v153 offset:3072
	ds_read_b128 v[168:171], v154
	ds_read_b128 v[172:175], v154 offset:1024
	ds_read_b128 v[176:179], v154 offset:2048
	ds_read_b128 v[180:183], v154 offset:3072
	s_add_u32 s0, s34, 0x40000
	s_addc_u32 s1, s35, 0
	s_mov_b32 m0, s40
	v_lshl_add_u64 v[226:227], s[0:1], 0, v[130:131]
	ds_read_b128 v[184:187], v151 offset:32768
	ds_read_b128 v[188:191], v151 offset:33792
	ds_read_b128 v[192:195], v151 offset:34816
	ds_read_b128 v[196:199], v151 offset:35840
	ds_read_b128 v[200:203], v151 offset:36864
	ds_read_b128 v[204:207], v151 offset:37888
	ds_read_b128 v[210:213], v151 offset:38912
	ds_read_b128 v[214:217], v151 offset:39936
	global_load_lds_dwordx4 v[226:227], off
	v_lshl_add_u64 v[226:227], s[0:1], 0, v[134:135]
	s_mov_b32 m0, s41
	s_nop 0
	global_load_lds_dwordx4 v[226:227], off
	s_waitcnt vmcnt(8)
	s_waitcnt lgkmcnt(0)
	s_barrier
	s_setprio 1
	v_mfma_f32_16x16x32_bf16 v[126:129], v[144:147], v[184:187], v[126:129]
	v_mfma_f32_16x16x32_bf16 v[122:125], v[160:163], v[184:187], v[122:125]
	v_mfma_f32_16x16x32_bf16 v[110:113], v[144:147], v[192:195], v[110:113]
	v_mfma_f32_16x16x32_bf16 v[106:109], v[160:163], v[192:195], v[106:109]
	v_mfma_f32_16x16x32_bf16 v[94:97], v[144:147], v[200:203], v[94:97]
	v_mfma_f32_16x16x32_bf16 v[90:93], v[160:163], v[200:203], v[90:93]
	v_mfma_f32_16x16x32_bf16 v[78:81], v[144:147], v[210:213], v[78:81]
	v_mfma_f32_16x16x32_bf16 v[74:77], v[160:163], v[210:213], v[74:77]
	v_mfma_f32_16x16x32_bf16 v[126:129], v[156:159], v[188:191], v[126:129]
	v_mfma_f32_16x16x32_bf16 v[122:125], v[164:167], v[188:191], v[122:125]
	v_mfma_f32_16x16x32_bf16 v[110:113], v[156:159], v[196:199], v[110:113]
	v_mfma_f32_16x16x32_bf16 v[106:109], v[164:167], v[196:199], v[106:109]
	v_mfma_f32_16x16x32_bf16 v[94:97], v[156:159], v[204:207], v[94:97]
	v_mfma_f32_16x16x32_bf16 v[90:93], v[164:167], v[204:207], v[90:93]
	v_mfma_f32_16x16x32_bf16 v[78:81], v[156:159], v[214:217], v[78:81]
	v_mfma_f32_16x16x32_bf16 v[74:77], v[164:167], v[214:217], v[74:77]
	s_setprio 0
	s_setprio 1
	v_mfma_f32_16x16x32_bf16 v[118:121], v[168:171], v[184:187], v[118:121]
	v_mfma_f32_16x16x32_bf16 v[114:117], v[176:179], v[184:187], v[114:117]
	v_mfma_f32_16x16x32_bf16 v[102:105], v[168:171], v[192:195], v[102:105]
	v_mfma_f32_16x16x32_bf16 v[98:101], v[176:179], v[192:195], v[98:101]
	v_mfma_f32_16x16x32_bf16 v[86:89], v[168:171], v[200:203], v[86:89]
	v_mfma_f32_16x16x32_bf16 v[82:85], v[176:179], v[200:203], v[82:85]
	v_mfma_f32_16x16x32_bf16 v[70:73], v[168:171], v[210:213], v[70:73]
	v_mfma_f32_16x16x32_bf16 v[66:69], v[176:179], v[210:213], v[66:69]
	v_mfma_f32_16x16x32_bf16 v[118:121], v[172:175], v[188:191], v[118:121]
	v_mfma_f32_16x16x32_bf16 v[114:117], v[180:183], v[188:191], v[114:117]
	v_mfma_f32_16x16x32_bf16 v[102:105], v[172:175], v[196:199], v[102:105]
	v_mfma_f32_16x16x32_bf16 v[98:101], v[180:183], v[196:199], v[98:101]
	v_mfma_f32_16x16x32_bf16 v[86:89], v[172:175], v[204:207], v[86:89]
	v_mfma_f32_16x16x32_bf16 v[82:85], v[180:183], v[204:207], v[82:85]
	v_mfma_f32_16x16x32_bf16 v[70:73], v[172:175], v[214:217], v[70:73]
	v_mfma_f32_16x16x32_bf16 v[66:69], v[180:183], v[214:217], v[66:69]
	s_setprio 0
	s_barrier
; #define PG8_STAGE(bufoff, gbase, voff) do { _Pragma("unroll") for (int _i = 0; _i < 2; ++_i) \
;         __builtin_amdgcn_global_load_lds((const unsigned*)((const char*)(gbase) + (voff)[_i]), (PG8_LAS unsigned*)(lds + (bufoff) + ldsw + _i * 8192), 16, 0, 0); } while (0)
; #define PG8_LDA(dst, b, h) do { _Pragma("unroll") for (int m = 0; m < 4; ++m) _Pragma("unroll") for (int k = 0; k < 2; ++k) dst[m][k] = *(const PG8_LAS bf16x8*)(lds + PG8_SA(b, h) + aoff + m * 2048 + k * 1024); } while (0)
; #define PG8_MMA(ai, bj, At, Bt) do { __builtin_amdgcn_s_setprio(1); _Pragma("unroll") for (int m = 0; m < 4; ++m) _Pragma("unroll") for (int n = 0; n < 2; ++n) _Pragma("unroll") for (int k = 0; k < 2; ++k) \
;         acc[ai][bj][m][n] = __builtin_amdgcn_mfma_f32_16x16x32_bf16(Bt[n][k], At[m][k], acc[ai][bj][m][n], 0, 0, 0); __builtin_amdgcn_s_setprio(0); } while (0)
; #define PG8_WAIT_V(n) asm volatile("s_waitcnt vmcnt(" #n ")" ::: "memory")
; #define PG8_WAIT_L(n) asm volatile("s_waitcnt lgkmcnt(" #n ")" ::: "memory")
; #define PG8_BAR __builtin_amdgcn_s_barrier()
; #define PG8_SCHED __builtin_amdgcn_sched_barrier(0)
; template <class Epi, class Sched, bool ALIGN_EPI = false, bool SP2 = false>
; __device__ __forceinline__ void gemm_phase(PG8_LAS unsigned char* lds, const Gemm g, const Sched& S, const Epi& E) {
;     ...
;             PG8_LDA(At, 1, 1); PG8_STAGE(PG8_SB(1, 0), b3, voffB); PG8_STAGE(PG8_SB(1, 1), b3 + hstep, voffB); PG8_STAGE(PG8_SA(1, 0), a3, voffA);
;             PG8_WAIT_V(8); PG8_WAIT_L(0); PG8_BAR; PG8_MMA(1, 0, At, B0); PG8_MMA(1, 1, At, B1); PG8_BAR; PG8_SCHED;
;     ...
;         if constexpr (ALIGN_EPI) { if (wr == 0) PG8_BAR; }
	s_add_i32 s0, s56, s36
	v_lshl_add_u64 v[218:219], v[218:219], 0, s[10:11]
	s_mov_b32 m0, s0
	ds_read_b128 v[184:187], v151 offset:49152
	ds_read_b128 v[188:191], v151 offset:50176
	ds_read_b128 v[192:195], v151 offset:51200
	ds_read_b128 v[196:199], v151 offset:52224
	ds_read_b128 v[200:203], v151 offset:53248
	ds_read_b128 v[204:207], v151 offset:54272
	ds_read_b128 v[210:213], v151 offset:55296
	ds_read_b128 v[214:217], v151 offset:56320
	global_load_lds_dwordx4 v[218:219], off
	s_add_i32 m0, s0, 0x2000
	s_add_u32 s0, s30, 0x40080
	v_lshl_add_u64 v[218:219], v[220:221], 0, s[10:11]
	s_addc_u32 s1, s31, 0
	s_add_i32 s30, s57, s36
	global_load_lds_dwordx4 v[218:219], off
	v_lshl_add_u64 v[218:219], s[0:1], 0, v[132:133]
	s_mov_b32 m0, s30
	s_nop 0
	global_load_lds_dwordx4 v[218:219], off
	v_lshl_add_u64 v[218:219], s[0:1], 0, v[136:137]
	s_add_i32 m0, s30, 0x2000
	s_nop 0
	global_load_lds_dwordx4 v[218:219], off
	v_lshl_add_u64 v[218:219], v[222:223], 0, s[10:11]
	s_mov_b32 m0, s48
	s_nop 0
	global_load_lds_dwordx4 v[218:219], off
	v_lshl_add_u64 v[218:219], v[224:225], 0, s[10:11]
	s_mov_b32 m0, s49
	s_nop 0
	global_load_lds_dwordx4 v[218:219], off
	s_waitcnt vmcnt(8)
	s_waitcnt lgkmcnt(0)
	s_barrier
	s_setprio 1
	v_mfma_f32_16x16x32_bf16 v[62:65], v[144:147], v[184:187], v[62:65]
	v_mfma_f32_16x16x32_bf16 v[58:61], v[160:163], v[184:187], v[58:61]
	v_mfma_f32_16x16x32_bf16 v[46:49], v[144:147], v[192:195], v[46:49]
	v_mfma_f32_16x16x32_bf16 v[42:45], v[160:163], v[192:195], v[42:45]
	v_mfma_f32_16x16x32_bf16 v[30:33], v[144:147], v[200:203], v[30:33]
	v_mfma_f32_16x16x32_bf16 v[26:29], v[160:163], v[200:203], v[26:29]
	v_mfma_f32_16x16x32_bf16 v[14:17], v[144:147], v[210:213], v[14:17]
	v_mfma_f32_16x16x32_bf16 v[10:13], v[160:163], v[210:213], v[10:13]
	v_mfma_f32_16x16x32_bf16 v[62:65], v[156:159], v[188:191], v[62:65]
	v_mfma_f32_16x16x32_bf16 v[58:61], v[164:167], v[188:191], v[58:61]
	v_mfma_f32_16x16x32_bf16 v[46:49], v[156:159], v[196:199], v[46:49]
	v_mfma_f32_16x16x32_bf16 v[42:45], v[164:167], v[196:199], v[42:45]
	v_mfma_f32_16x16x32_bf16 v[30:33], v[156:159], v[204:207], v[30:33]
	v_mfma_f32_16x16x32_bf16 v[26:29], v[164:167], v[204:207], v[26:29]
	v_mfma_f32_16x16x32_bf16 v[14:17], v[156:159], v[214:217], v[14:17]
	v_mfma_f32_16x16x32_bf16 v[10:13], v[164:167], v[214:217], v[10:13]
	s_setprio 0
	s_setprio 1
	v_mfma_f32_16x16x32_bf16 v[54:57], v[168:171], v[184:187], v[54:57]
	v_mfma_f32_16x16x32_bf16 v[50:53], v[176:179], v[184:187], v[50:53]
	v_mfma_f32_16x16x32_bf16 v[38:41], v[168:171], v[192:195], v[38:41]
	v_mfma_f32_16x16x32_bf16 v[34:37], v[176:179], v[192:195], v[34:37]
	v_mfma_f32_16x16x32_bf16 v[22:25], v[168:171], v[200:203], v[22:25]
	v_mfma_f32_16x16x32_bf16 v[18:21], v[176:179], v[200:203], v[18:21]
	v_mfma_f32_16x16x32_bf16 v[6:9], v[168:171], v[210:213], v[6:9]
	v_mfma_f32_16x16x32_bf16 v[2:5], v[176:179], v[210:213], v[2:5]
	v_mfma_f32_16x16x32_bf16 v[54:57], v[172:175], v[188:191], v[54:57]
	v_mfma_f32_16x16x32_bf16 v[50:53], v[180:183], v[188:191], v[50:53]
	v_mfma_f32_16x16x32_bf16 v[38:41], v[172:175], v[196:199], v[38:41]
	v_mfma_f32_16x16x32_bf16 v[34:37], v[180:183], v[196:199], v[34:37]
	v_mfma_f32_16x16x32_bf16 v[22:25], v[172:175], v[204:207], v[22:25]
	v_mfma_f32_16x16x32_bf16 v[18:21], v[180:183], v[204:207], v[18:21]
	v_mfma_f32_16x16x32_bf16 v[6:9], v[172:175], v[214:217], v[6:9]
	v_mfma_f32_16x16x32_bf16 v[2:5], v[180:183], v[214:217], v[2:5]
	s_setprio 0
	s_barrier
	s_add_i32 s73, s73, 2
	s_add_u32 s28, s28, 0x100
	s_addc_u32 s29, s29, 0
	s_add_u32 s69, s69, 0x100
	s_addc_u32 s72, s72, 0
	s_cmp_gt_u32 s73, 13
	s_cbranch_scc0 .LBB0_1267
	s_and_b64 vcc, exec, s[12:13]
	s_cbranch_vccz .LBB0_1270
	s_barrier

; #define PG8_STAGE(bufoff, gbase, voff) do { _Pragma("unroll") for (int _i = 0; _i < 2; ++_i) \
;         __builtin_amdgcn_global_load_lds((const unsigned*)((const char*)(gbase) + (voff)[_i]), (PG8_LAS unsigned*)(lds + (bufoff) + ldsw + _i * 8192), 16, 0, 0); } while (0)
; #define PG8_LDA(dst, b, h) do { _Pragma("unroll") for (int m = 0; m < 4; ++m) _Pragma("unroll") for (int k = 0; k < 2; ++k) dst[m][k] = *(const PG8_LAS bf16x8*)(lds + PG8_SA(b, h) + aoff + m * 2048 + k * 1024); } while (0)
; #define PG8_LDB(dst, b, h) do { _Pragma("unroll") for (int n = 0; n < 2; ++n) _Pragma("unroll") for (int k = 0; k < 2; ++k) dst[n][k] = *(const PG8_LAS bf16x8*)(lds + PG8_SB(b, h) + boff + n * 2048 + k * 1024); } while (0)
; #define PG8_MMA(ai, bj, At, Bt) do { __builtin_amdgcn_s_setprio(1); _Pragma("unroll") for (int m = 0; m < 4; ++m) _Pragma("unroll") for (int n = 0; n < 2; ++n) _Pragma("unroll") for (int k = 0; k < 2; ++k) \
;         acc[ai][bj][m][n] = __builtin_amdgcn_mfma_f32_16x16x32_bf16(Bt[n][k], At[m][k], acc[ai][bj][m][n], 0, 0, 0); __builtin_amdgcn_s_setprio(0); } while (0)
; #define PG8_WAIT_V(n) asm volatile("s_waitcnt vmcnt(" #n ")" ::: "memory")
; #define PG8_WAIT_L(n) asm volatile("s_waitcnt lgkmcnt(" #n ")" ::: "memory")
; #define PG8_BAR __builtin_amdgcn_s_barrier()
; #define PG8_SCHED __builtin_amdgcn_sched_barrier(0)
; template <class Epi, class Sched, bool ALIGN_EPI = false, bool SP2 = false>
; __device__ __forceinline__ void gemm_phase(PG8_LAS unsigned char* lds, const Gemm g, const Sched& S, const Epi& E) {
;     ...
;             const bool last = (t == nt - 2);
;             const char* a1 = cA + (size_t)(t + 1) * kstep;
;             const char* a2 = last ? nA : cA + (size_t)(t + 2) * kstep; const char* b2 = last ? nB : cB + (size_t)(t + 2) * kstep;
;             const char* a3 = a2 + kstep; const char* b3 = b2 + kstep;
;             if (last && has_next) S.a_ready(nxt);
;             if constexpr (SP2) {
;             PG8_LDB(B0, 0, 0); PG8_LDB(B1, 0, 1); PG8_SCHED; PG8_LDA(At, 0, 0); PG8_STAGE(PG8_SA(1, 1), a1 + hstep, voffA);
;             PG8_WAIT_V(8); PG8_WAIT_L(0); PG8_BAR; PG8_MMA(0, 0, At, B0); PG8_MMA(0, 1, At, B1); PG8_BAR; PG8_SCHED;
;             PG8_LDA(At, 0, 1); PG8_STAGE(PG8_SB(0, 0), b2, voffB); PG8_STAGE(PG8_SB(0, 1), b2 + hstep, voffB); PG8_STAGE(PG8_SA(0, 0), a2, voffA);
.LBB0_1380:
	ds_read_b128 v[146:149], v153
	ds_read_b128 v[160:163], v153 offset:1024
	ds_read_b128 v[164:167], v153 offset:2048
	ds_read_b128 v[168:171], v153 offset:3072
	ds_read_b128 v[172:175], v154
	ds_read_b128 v[176:179], v154 offset:1024
	ds_read_b128 v[180:183], v154 offset:2048
	ds_read_b128 v[184:187], v154 offset:3072
	s_add_u32 s0, s4, 0xfffc0080
	s_addc_u32 s1, s5, -1
	s_cmp_eq_u32 s54, 12
	s_cselect_b32 s29, s15, s1
	s_cselect_b32 s28, s25, s0
	s_cselect_b32 s27, s9, s53
	s_cselect_b32 s26, s49, s52
	v_lshl_add_u64 v[222:223], s[4:5], 0, v[140:141]
	s_add_i32 m0, s34, 0xc000
	ds_read_b128 v[188:191], v155
	ds_read_b128 v[192:195], v155 offset:1024
	ds_read_b128 v[196:199], v155 offset:2048
	ds_read_b128 v[200:203], v155 offset:3072
	ds_read_b128 v[204:207], v155 offset:4096
	ds_read_b128 v[210:213], v155 offset:5120
	ds_read_b128 v[214:217], v155 offset:6144
	ds_read_b128 v[218:221], v155 offset:7168
	global_load_lds_dwordx4 v[222:223], off
	v_lshl_add_u64 v[222:223], s[4:5], 0, v[142:143]
	s_add_i32 m0, s34, 0xe000
	s_nop 0
	global_load_lds_dwordx4 v[222:223], off
	s_waitcnt vmcnt(8)
	s_waitcnt lgkmcnt(0)
	s_barrier
	s_setprio 1
	v_mfma_f32_16x16x32_bf16 v[126:129], v[146:149], v[188:191], v[126:129]
	v_mfma_f32_16x16x32_bf16 v[122:125], v[164:167], v[188:191], v[122:125]
	v_mfma_f32_16x16x32_bf16 v[110:113], v[146:149], v[196:199], v[110:113]
	v_mfma_f32_16x16x32_bf16 v[106:109], v[164:167], v[196:199], v[106:109]
	v_mfma_f32_16x16x32_bf16 v[94:97], v[146:149], v[204:207], v[94:97]
	v_mfma_f32_16x16x32_bf16 v[90:93], v[164:167], v[204:207], v[90:93]
	v_mfma_f32_16x16x32_bf16 v[78:81], v[146:149], v[214:217], v[78:81]
	v_mfma_f32_16x16x32_bf16 v[74:77], v[164:167], v[214:217], v[74:77]
	v_mfma_f32_16x16x32_bf16 v[126:129], v[160:163], v[192:195], v[126:129]
	v_mfma_f32_16x16x32_bf16 v[122:125], v[168:171], v[192:195], v[122:125]
	v_mfma_f32_16x16x32_bf16 v[110:113], v[160:163], v[200:203], v[110:113]
	v_mfma_f32_16x16x32_bf16 v[106:109], v[168:171], v[200:203], v[106:109]
	v_mfma_f32_16x16x32_bf16 v[94:97], v[160:163], v[210:213], v[94:97]
	v_mfma_f32_16x16x32_bf16 v[90:93], v[168:171], v[210:213], v[90:93]
	v_mfma_f32_16x16x32_bf16 v[78:81], v[160:163], v[218:221], v[78:81]
	v_mfma_f32_16x16x32_bf16 v[74:77], v[168:171], v[218:221], v[74:77]
	s_setprio 0
	s_setprio 1
	v_mfma_f32_16x16x32_bf16 v[118:121], v[172:175], v[188:191], v[118:121]
	v_mfma_f32_16x16x32_bf16 v[114:117], v[180:183], v[188:191], v[114:117]
	v_mfma_f32_16x16x32_bf16 v[102:105], v[172:175], v[196:199], v[102:105]
	v_mfma_f32_16x16x32_bf16 v[98:101], v[180:183], v[196:199], v[98:101]
	v_mfma_f32_16x16x32_bf16 v[86:89], v[172:175], v[204:207], v[86:89]
	v_mfma_f32_16x16x32_bf16 v[82:85], v[180:183], v[204:207], v[82:85]
	v_mfma_f32_16x16x32_bf16 v[70:73], v[172:175], v[214:217], v[70:73]
	v_mfma_f32_16x16x32_bf16 v[66:69], v[180:183], v[214:217], v[66:69]
	v_mfma_f32_16x16x32_bf16 v[118:121], v[176:179], v[192:195], v[118:121]
	v_mfma_f32_16x16x32_bf16 v[114:117], v[184:187], v[192:195], v[114:117]
	v_mfma_f32_16x16x32_bf16 v[102:105], v[176:179], v[200:203], v[102:105]
	v_mfma_f32_16x16x32_bf16 v[98:101], v[184:187], v[200:203], v[98:101]
	v_mfma_f32_16x16x32_bf16 v[86:89], v[176:179], v[210:213], v[86:89]
	v_mfma_f32_16x16x32_bf16 v[82:85], v[184:187], v[210:213], v[82:85]
	v_mfma_f32_16x16x32_bf16 v[70:73], v[176:179], v[218:221], v[70:73]
	v_mfma_f32_16x16x32_bf16 v[66:69], v[184:187], v[218:221], v[66:69]
	s_setprio 0
	s_barrier
	s_add_i32 s0, s41, s31
	v_lshl_add_u64 v[222:223], s[26:27], 0, v[132:133]
	s_mov_b32 m0, s0
	ds_read_b128 v[188:191], v155 offset:16384
	ds_read_b128 v[192:195], v155 offset:17408
	ds_read_b128 v[196:199], v155 offset:18432
	ds_read_b128 v[200:203], v155 offset:19456
	ds_read_b128 v[204:207], v155 offset:20480
	ds_read_b128 v[210:213], v155 offset:21504
	ds_read_b128 v[214:217], v155 offset:22528
	ds_read_b128 v[218:221], v155 offset:23552
	global_load_lds_dwordx4 v[222:223], off
	s_add_i32 m0, s0, 0x2000
	s_add_u32 s0, s26, 0x40000
	v_lshl_add_u64 v[224:225], s[26:27], 0, v[136:137]
	s_addc_u32 s1, s27, 0
	s_add_i32 s55, s44, s31
	global_load_lds_dwordx4 v[224:225], off
	v_lshl_add_u64 v[226:227], s[0:1], 0, v[132:133]
	s_mov_b32 m0, s55
	v_lshl_add_u64 v[228:229], s[28:29], 0, v[134:135]
	global_load_lds_dwordx4 v[226:227], off
	v_lshl_add_u64 v[226:227], s[0:1], 0, v[136:137]
	s_add_i32 m0, s55, 0x2000
	s_nop 0
	global_load_lds_dwordx4 v[226:227], off
	v_lshl_add_u64 v[226:227], s[28:29], 0, v[130:131]
	s_mov_b32 m0, s34
	s_nop 0
	global_load_lds_dwordx4 v[226:227], off
	s_mov_b32 m0, s35
	s_nop 0
	global_load_lds_dwordx4 v[228:229], off
	s_waitcnt vmcnt(8)
	s_waitcnt lgkmcnt(0)
	s_barrier
; #define PG8_STAGE(bufoff, gbase, voff) do { _Pragma("unroll") for (int _i = 0; _i < 2; ++_i) \
;         __builtin_amdgcn_global_load_lds((const unsigned*)((const char*)(gbase) + (voff)[_i]), (PG8_LAS unsigned*)(lds + (bufoff) + ldsw + _i * 8192), 16, 0, 0); } while (0)
; #define PG8_LDA(dst, b, h) do { _Pragma("unroll") for (int m = 0; m < 4; ++m) _Pragma("unroll") for (int k = 0; k < 2; ++k) dst[m][k] = *(const PG8_LAS bf16x8*)(lds + PG8_SA(b, h) + aoff + m * 2048 + k * 1024); } while (0)
; #define PG8_LDB(dst, b, h) do { _Pragma("unroll") for (int n = 0; n < 2; ++n) _Pragma("unroll") for (int k = 0; k < 2; ++k) dst[n][k] = *(const PG8_LAS bf16x8*)(lds + PG8_SB(b, h) + boff + n * 2048 + k * 1024); } while (0)
; #define PG8_MMA(ai, bj, At, Bt) do { __builtin_amdgcn_s_setprio(1); _Pragma("unroll") for (int m = 0; m < 4; ++m) _Pragma("unroll") for (int n = 0; n < 2; ++n) _Pragma("unroll") for (int k = 0; k < 2; ++k) \
;         acc[ai][bj][m][n] = __builtin_amdgcn_mfma_f32_16x16x32_bf16(Bt[n][k], At[m][k], acc[ai][bj][m][n], 0, 0, 0); __builtin_amdgcn_s_setprio(0); } while (0)
; #define PG8_WAIT_V(n) asm volatile("s_waitcnt vmcnt(" #n ")" ::: "memory")
; #define PG8_WAIT_L(n) asm volatile("s_waitcnt lgkmcnt(" #n ")" ::: "memory")
; #define PG8_BAR __builtin_amdgcn_s_barrier()
; #define PG8_SCHED __builtin_amdgcn_sched_barrier(0)
; template <class Epi, class Sched, bool ALIGN_EPI = false, bool SP2 = false>
; __device__ __forceinline__ void gemm_phase(PG8_LAS unsigned char* lds, const Gemm g, const Sched& S, const Epi& E) {
;     ...
;             PG8_WAIT_V(8); PG8_WAIT_L(0); PG8_BAR; PG8_MMA(1, 0, At, B0); PG8_MMA(1, 1, At, B1); PG8_BAR; PG8_SCHED;
;             PG8_LDB(B0, 1, 0); PG8_LDB(B1, 1, 1); PG8_SCHED; PG8_LDA(At, 1, 0); PG8_STAGE(PG8_SA(0, 1), a2 + hstep, voffA);
;             PG8_WAIT_V(8); PG8_WAIT_L(0); PG8_BAR; PG8_MMA(0, 0, At, B0); PG8_MMA(0, 1, At, B1); PG8_BAR; PG8_SCHED;
	s_setprio 1
	v_mfma_f32_16x16x32_bf16 v[62:65], v[146:149], v[188:191], v[62:65]
	v_mfma_f32_16x16x32_bf16 v[58:61], v[164:167], v[188:191], v[58:61]
	v_mfma_f32_16x16x32_bf16 v[46:49], v[146:149], v[196:199], v[46:49]
	v_mfma_f32_16x16x32_bf16 v[42:45], v[164:167], v[196:199], v[42:45]
	v_mfma_f32_16x16x32_bf16 v[30:33], v[146:149], v[204:207], v[30:33]
	v_mfma_f32_16x16x32_bf16 v[26:29], v[164:167], v[204:207], v[26:29]
	v_mfma_f32_16x16x32_bf16 v[14:17], v[146:149], v[214:217], v[14:17]
	v_mfma_f32_16x16x32_bf16 v[10:13], v[164:167], v[214:217], v[10:13]
	v_mfma_f32_16x16x32_bf16 v[62:65], v[160:163], v[192:195], v[62:65]
	v_mfma_f32_16x16x32_bf16 v[58:61], v[168:171], v[192:195], v[58:61]
	v_mfma_f32_16x16x32_bf16 v[46:49], v[160:163], v[200:203], v[46:49]
	v_mfma_f32_16x16x32_bf16 v[42:45], v[168:171], v[200:203], v[42:45]
	v_mfma_f32_16x16x32_bf16 v[30:33], v[160:163], v[210:213], v[30:33]
	v_mfma_f32_16x16x32_bf16 v[26:29], v[168:171], v[210:213], v[26:29]
	v_mfma_f32_16x16x32_bf16 v[14:17], v[160:163], v[218:221], v[14:17]
	v_mfma_f32_16x16x32_bf16 v[10:13], v[168:171], v[218:221], v[10:13]
	s_setprio 0
	s_setprio 1
	v_mfma_f32_16x16x32_bf16 v[54:57], v[172:175], v[188:191], v[54:57]
	v_mfma_f32_16x16x32_bf16 v[50:53], v[180:183], v[188:191], v[50:53]
	v_mfma_f32_16x16x32_bf16 v[38:41], v[172:175], v[196:199], v[38:41]
	v_mfma_f32_16x16x32_bf16 v[34:37], v[180:183], v[196:199], v[34:37]
	v_mfma_f32_16x16x32_bf16 v[22:25], v[172:175], v[204:207], v[22:25]
	v_mfma_f32_16x16x32_bf16 v[18:21], v[180:183], v[204:207], v[18:21]
	v_mfma_f32_16x16x32_bf16 v[6:9], v[172:175], v[214:217], v[6:9]
	v_mfma_f32_16x16x32_bf16 v[2:5], v[180:183], v[214:217], v[2:5]
	v_mfma_f32_16x16x32_bf16 v[54:57], v[176:179], v[192:195], v[54:57]
	v_mfma_f32_16x16x32_bf16 v[50:53], v[184:187], v[192:195], v[50:53]
	v_mfma_f32_16x16x32_bf16 v[38:41], v[176:179], v[200:203], v[38:41]
	v_mfma_f32_16x16x32_bf16 v[34:37], v[184:187], v[200:203], v[34:37]
	v_mfma_f32_16x16x32_bf16 v[22:25], v[176:179], v[210:213], v[22:25]
	v_mfma_f32_16x16x32_bf16 v[18:21], v[184:187], v[210:213], v[18:21]
	v_mfma_f32_16x16x32_bf16 v[6:9], v[176:179], v[218:221], v[6:9]
	v_mfma_f32_16x16x32_bf16 v[2:5], v[184:187], v[218:221], v[2:5]
	s_setprio 0
	s_barrier
	ds_read_b128 v[146:149], v157
	ds_read_b128 v[160:163], v157 offset:1024
	ds_read_b128 v[164:167], v157 offset:2048
	ds_read_b128 v[168:171], v157 offset:3072
	ds_read_b128 v[172:175], v158
	ds_read_b128 v[176:179], v158 offset:1024
	ds_read_b128 v[180:183], v158 offset:2048
	ds_read_b128 v[184:187], v158 offset:3072
	s_add_u32 s0, s28, 0x40000
	s_addc_u32 s1, s29, 0
	s_mov_b32 m0, s36
	v_lshl_add_u64 v[230:231], s[0:1], 0, v[130:131]
	ds_read_b128 v[188:191], v155 offset:32768
	ds_read_b128 v[192:195], v155 offset:33792
	ds_read_b128 v[196:199], v155 offset:34816
	ds_read_b128 v[200:203], v155 offset:35840
	ds_read_b128 v[204:207], v155 offset:36864
	ds_read_b128 v[210:213], v155 offset:37888
	ds_read_b128 v[214:217], v155 offset:38912
	ds_read_b128 v[218:221], v155 offset:39936
	global_load_lds_dwordx4 v[230:231], off
	v_lshl_add_u64 v[230:231], s[0:1], 0, v[134:135]
	s_mov_b32 m0, s37
	s_nop 0
	global_load_lds_dwordx4 v[230:231], off
	s_waitcnt vmcnt(8)
	s_waitcnt lgkmcnt(0)
	s_barrier
	s_setprio 1
	v_mfma_f32_16x16x32_bf16 v[126:129], v[146:149], v[188:191], v[126:129]
	v_mfma_f32_16x16x32_bf16 v[122:125], v[164:167], v[188:191], v[122:125]
	v_mfma_f32_16x16x32_bf16 v[110:113], v[146:149], v[196:199], v[110:113]
	v_mfma_f32_16x16x32_bf16 v[106:109], v[164:167], v[196:199], v[106:109]
	v_mfma_f32_16x16x32_bf16 v[94:97], v[146:149], v[204:207], v[94:97]
	v_mfma_f32_16x16x32_bf16 v[90:93], v[164:167], v[204:207], v[90:93]
	v_mfma_f32_16x16x32_bf16 v[78:81], v[146:149], v[214:217], v[78:81]
	v_mfma_f32_16x16x32_bf16 v[74:77], v[164:167], v[214:217], v[74:77]
	v_mfma_f32_16x16x32_bf16 v[126:129], v[160:163], v[192:195], v[126:129]
	v_mfma_f32_16x16x32_bf16 v[122:125], v[168:171], v[192:195], v[122:125]
	v_mfma_f32_16x16x32_bf16 v[110:113], v[160:163], v[200:203], v[110:113]
	v_mfma_f32_16x16x32_bf16 v[106:109], v[168:171], v[200:203], v[106:109]
	v_mfma_f32_16x16x32_bf16 v[94:97], v[160:163], v[210:213], v[94:97]
	v_mfma_f32_16x16x32_bf16 v[90:93], v[168:171], v[210:213], v[90:93]
	v_mfma_f32_16x16x32_bf16 v[78:81], v[160:163], v[218:221], v[78:81]
	v_mfma_f32_16x16x32_bf16 v[74:77], v[168:171], v[218:221], v[74:77]
	s_setprio 0
	s_setprio 1
	v_mfma_f32_16x16x32_bf16 v[118:121], v[172:175], v[188:191], v[118:121]
	v_mfma_f32_16x16x32_bf16 v[114:117], v[180:183], v[188:191], v[114:117]
	v_mfma_f32_16x16x32_bf16 v[102:105], v[172:175], v[196:199], v[102:105]
	v_mfma_f32_16x16x32_bf16 v[98:101], v[180:183], v[196:199], v[98:101]
	v_mfma_f32_16x16x32_bf16 v[86:89], v[172:175], v[204:207], v[86:89]
	v_mfma_f32_16x16x32_bf16 v[82:85], v[180:183], v[204:207], v[82:85]
	v_mfma_f32_16x16x32_bf16 v[70:73], v[172:175], v[214:217], v[70:73]
	v_mfma_f32_16x16x32_bf16 v[66:69], v[180:183], v[214:217], v[66:69]
	v_mfma_f32_16x16x32_bf16 v[118:121], v[176:179], v[192:195], v[118:121]
	v_mfma_f32_16x16x32_bf16 v[114:117], v[184:187], v[192:195], v[114:117]
	v_mfma_f32_16x16x32_bf16 v[102:105], v[176:179], v[200:203], v[102:105]
	v_mfma_f32_16x16x32_bf16 v[98:101], v[184:187], v[200:203], v[98:101]
	v_mfma_f32_16x16x32_bf16 v[86:89], v[176:179], v[210:213], v[86:89]
	v_mfma_f32_16x16x32_bf16 v[82:85], v[184:187], v[210:213], v[82:85]
	v_mfma_f32_16x16x32_bf16 v[70:73], v[176:179], v[218:221], v[70:73]
	v_mfma_f32_16x16x32_bf16 v[66:69], v[184:187], v[218:221], v[66:69]
	s_setprio 0
	s_barrier
; #define PG8_STAGE(bufoff, gbase, voff) do { _Pragma("unroll") for (int _i = 0; _i < 2; ++_i) \
;         __builtin_amdgcn_global_load_lds((const unsigned*)((const char*)(gbase) + (voff)[_i]), (PG8_LAS unsigned*)(lds + (bufoff) + ldsw + _i * 8192), 16, 0, 0); } while (0)
; #define PG8_LDA(dst, b, h) do { _Pragma("unroll") for (int m = 0; m < 4; ++m) _Pragma("unroll") for (int k = 0; k < 2; ++k) dst[m][k] = *(const PG8_LAS bf16x8*)(lds + PG8_SA(b, h) + aoff + m * 2048 + k * 1024); } while (0)
; #define PG8_MMA(ai, bj, At, Bt) do { __builtin_amdgcn_s_setprio(1); _Pragma("unroll") for (int m = 0; m < 4; ++m) _Pragma("unroll") for (int n = 0; n < 2; ++n) _Pragma("unroll") for (int k = 0; k < 2; ++k) \
;         acc[ai][bj][m][n] = __builtin_amdgcn_mfma_f32_16x16x32_bf16(Bt[n][k], At[m][k], acc[ai][bj][m][n], 0, 0, 0); __builtin_amdgcn_s_setprio(0); } while (0)
; #define PG8_WAIT_V(n) asm volatile("s_waitcnt vmcnt(" #n ")" ::: "memory")
; #define PG8_WAIT_L(n) asm volatile("s_waitcnt lgkmcnt(" #n ")" ::: "memory")
; #define PG8_BAR __builtin_amdgcn_s_barrier()
; #define PG8_SCHED __builtin_amdgcn_sched_barrier(0)
; template <class Epi, class Sched, bool ALIGN_EPI = false, bool SP2 = false>
; __device__ __forceinline__ void gemm_phase(PG8_LAS unsigned char* lds, const Gemm g, const Sched& S, const Epi& E) {
;     ...
;             PG8_LDA(At, 1, 1); PG8_STAGE(PG8_SB(1, 0), b3, voffB); PG8_STAGE(PG8_SB(1, 1), b3 + hstep, voffB); PG8_STAGE(PG8_SA(1, 0), a3, voffA);
;             PG8_WAIT_V(8); PG8_WAIT_L(0); PG8_BAR; PG8_MMA(1, 0, At, B0); PG8_MMA(1, 1, At, B1); PG8_BAR; PG8_SCHED;
;     ...
;         if constexpr (ALIGN_EPI) { if (wr == 0) PG8_BAR; }
	s_add_i32 s0, s45, s31
	v_lshl_add_u64 v[222:223], v[222:223], 0, s[10:11]
	s_mov_b32 m0, s0
	ds_read_b128 v[188:191], v155 offset:49152
	ds_read_b128 v[192:195], v155 offset:50176
	ds_read_b128 v[196:199], v155 offset:51200
	ds_read_b128 v[200:203], v155 offset:52224
	ds_read_b128 v[204:207], v155 offset:53248
	ds_read_b128 v[210:213], v155 offset:54272
	ds_read_b128 v[214:217], v155 offset:55296
	ds_read_b128 v[218:221], v155 offset:56320
	global_load_lds_dwordx4 v[222:223], off
	s_add_i32 m0, s0, 0x2000
	s_add_u32 s0, s26, 0x40080
	v_lshl_add_u64 v[222:223], v[224:225], 0, s[10:11]
	s_addc_u32 s1, s27, 0
	s_add_i32 s26, s46, s31
	global_load_lds_dwordx4 v[222:223], off
	v_lshl_add_u64 v[222:223], s[0:1], 0, v[132:133]
	s_mov_b32 m0, s26
	s_nop 0
	global_load_lds_dwordx4 v[222:223], off
	v_lshl_add_u64 v[222:223], s[0:1], 0, v[136:137]
	s_add_i32 m0, s26, 0x2000
	s_nop 0
	global_load_lds_dwordx4 v[222:223], off
	v_lshl_add_u64 v[222:223], v[226:227], 0, s[10:11]
	s_mov_b32 m0, s38
	s_nop 0
	global_load_lds_dwordx4 v[222:223], off
	v_lshl_add_u64 v[222:223], v[228:229], 0, s[10:11]
	s_mov_b32 m0, s39
	s_nop 0
	global_load_lds_dwordx4 v[222:223], off
	s_waitcnt vmcnt(8)
	s_waitcnt lgkmcnt(0)
	s_barrier
	s_setprio 1
	v_mfma_f32_16x16x32_bf16 v[62:65], v[146:149], v[188:191], v[62:65]
	v_mfma_f32_16x16x32_bf16 v[58:61], v[164:167], v[188:191], v[58:61]
	v_mfma_f32_16x16x32_bf16 v[46:49], v[146:149], v[196:199], v[46:49]
	v_mfma_f32_16x16x32_bf16 v[42:45], v[164:167], v[196:199], v[42:45]
	v_mfma_f32_16x16x32_bf16 v[30:33], v[146:149], v[204:207], v[30:33]
	v_mfma_f32_16x16x32_bf16 v[26:29], v[164:167], v[204:207], v[26:29]
	v_mfma_f32_16x16x32_bf16 v[14:17], v[146:149], v[214:217], v[14:17]
	v_mfma_f32_16x16x32_bf16 v[10:13], v[164:167], v[214:217], v[10:13]
	v_mfma_f32_16x16x32_bf16 v[62:65], v[160:163], v[192:195], v[62:65]
	v_mfma_f32_16x16x32_bf16 v[58:61], v[168:171], v[192:195], v[58:61]
	v_mfma_f32_16x16x32_bf16 v[46:49], v[160:163], v[200:203], v[46:49]
	v_mfma_f32_16x16x32_bf16 v[42:45], v[168:171], v[200:203], v[42:45]
	v_mfma_f32_16x16x32_bf16 v[30:33], v[160:163], v[210:213], v[30:33]
	v_mfma_f32_16x16x32_bf16 v[26:29], v[168:171], v[210:213], v[26:29]
	v_mfma_f32_16x16x32_bf16 v[14:17], v[160:163], v[218:221], v[14:17]
	v_mfma_f32_16x16x32_bf16 v[10:13], v[168:171], v[218:221], v[10:13]
	s_setprio 0
	s_setprio 1
	v_mfma_f32_16x16x32_bf16 v[54:57], v[172:175], v[188:191], v[54:57]
	v_mfma_f32_16x16x32_bf16 v[50:53], v[180:183], v[188:191], v[50:53]
	v_mfma_f32_16x16x32_bf16 v[38:41], v[172:175], v[196:199], v[38:41]
	v_mfma_f32_16x16x32_bf16 v[34:37], v[180:183], v[196:199], v[34:37]
	v_mfma_f32_16x16x32_bf16 v[22:25], v[172:175], v[204:207], v[22:25]
	v_mfma_f32_16x16x32_bf16 v[18:21], v[180:183], v[204:207], v[18:21]
	v_mfma_f32_16x16x32_bf16 v[6:9], v[172:175], v[214:217], v[6:9]
	v_mfma_f32_16x16x32_bf16 v[2:5], v[180:183], v[214:217], v[2:5]
	v_mfma_f32_16x16x32_bf16 v[54:57], v[176:179], v[192:195], v[54:57]
	v_mfma_f32_16x16x32_bf16 v[50:53], v[184:187], v[192:195], v[50:53]
	v_mfma_f32_16x16x32_bf16 v[38:41], v[176:179], v[200:203], v[38:41]
	v_mfma_f32_16x16x32_bf16 v[34:37], v[184:187], v[200:203], v[34:37]
	v_mfma_f32_16x16x32_bf16 v[22:25], v[176:179], v[210:213], v[22:25]
	v_mfma_f32_16x16x32_bf16 v[18:21], v[184:187], v[210:213], v[18:21]
	v_mfma_f32_16x16x32_bf16 v[6:9], v[176:179], v[218:221], v[6:9]
	v_mfma_f32_16x16x32_bf16 v[2:5], v[184:187], v[218:221], v[2:5]
	s_setprio 0
	s_barrier
	s_add_i32 s54, s54, 2
	s_add_u32 s4, s4, 0x100
	s_addc_u32 s5, s5, 0
	s_add_u32 s52, s52, 0x100
	s_addc_u32 s53, s53, 0
	s_cmp_gt_u32 s54, 13
	s_cbranch_scc0 .LBB0_1380
	s_and_b64 vcc, exec, s[12:13]
	s_cbranch_vccz .LBB0_1383
	s_barrier

; #define PG8_STAGE(bufoff, gbase, voff) do { _Pragma("unroll") for (int _i = 0; _i < 2; ++_i) \
;         __builtin_amdgcn_global_load_lds((const unsigned*)((const char*)(gbase) + (voff)[_i]), (PG8_LAS unsigned*)(lds + (bufoff) + ldsw + _i * 8192), 16, 0, 0); } while (0)
; #define PG8_LDA(dst, b, h) do { _Pragma("unroll") for (int m = 0; m < 4; ++m) _Pragma("unroll") for (int k = 0; k < 2; ++k) dst[m][k] = *(const PG8_LAS bf16x8*)(lds + PG8_SA(b, h) + aoff + m * 2048 + k * 1024); } while (0)
; #define PG8_LDB(dst, b, h) do { _Pragma("unroll") for (int n = 0; n < 2; ++n) _Pragma("unroll") for (int k = 0; k < 2; ++k) dst[n][k] = *(const PG8_LAS bf16x8*)(lds + PG8_SB(b, h) + boff + n * 2048 + k * 1024); } while (0)
; #define PG8_MMA(ai, bj, At, Bt) do { __builtin_amdgcn_s_setprio(1); _Pragma("unroll") for (int m = 0; m < 4; ++m) _Pragma("unroll") for (int n = 0; n < 2; ++n) _Pragma("unroll") for (int k = 0; k < 2; ++k) \
;         acc[ai][bj][m][n] = __builtin_amdgcn_mfma_f32_16x16x32_bf16(Bt[n][k], At[m][k], acc[ai][bj][m][n], 0, 0, 0); __builtin_amdgcn_s_setprio(0); } while (0)
; #define PG8_WAIT_V(n) asm volatile("s_waitcnt vmcnt(" #n ")" ::: "memory")
; #define PG8_WAIT_L(n) asm volatile("s_waitcnt lgkmcnt(" #n ")" ::: "memory")
; #define PG8_BAR __builtin_amdgcn_s_barrier()
; #define PG8_SCHED __builtin_amdgcn_sched_barrier(0)
; template <class Epi, class Sched, bool ALIGN_EPI = false, bool SP2 = false>
; __device__ __forceinline__ void gemm_phase(PG8_LAS unsigned char* lds, const Gemm g, const Sched& S, const Epi& E) {
;     ...
;             const bool last = (t == nt - 2);
;             const char* a1 = cA + (size_t)(t + 1) * kstep;
;             const char* a2 = last ? nA : cA + (size_t)(t + 2) * kstep; const char* b2 = last ? nB : cB + (size_t)(t + 2) * kstep;
;             const char* a3 = a2 + kstep; const char* b3 = b2 + kstep;
;             if (last && has_next) S.a_ready(nxt);
;             if constexpr (SP2) {
;             PG8_LDB(B0, 0, 0); PG8_LDB(B1, 0, 1); PG8_SCHED; PG8_LDA(At, 0, 0); PG8_STAGE(PG8_SA(1, 1), a1 + hstep, voffA);
;             PG8_WAIT_V(8); PG8_WAIT_L(0); PG8_BAR; PG8_MMA(0, 0, At, B0); PG8_MMA(0, 1, At, B1); PG8_BAR; PG8_SCHED;
;             PG8_LDA(At, 0, 1); PG8_STAGE(PG8_SB(0, 0), b2, voffB); PG8_STAGE(PG8_SB(0, 1), b2 + hstep, voffB); PG8_STAGE(PG8_SA(0, 0), a2, voffA);
.LBB0_1498:
	ds_read_b128 v[142:145], v148
	ds_read_b128 v[154:157], v148 offset:1024
	ds_read_b128 v[158:161], v148 offset:2048
	ds_read_b128 v[162:165], v148 offset:3072
	ds_read_b128 v[166:169], v149
	ds_read_b128 v[170:173], v149 offset:1024
	ds_read_b128 v[174:177], v149 offset:2048
	ds_read_b128 v[178:181], v149 offset:3072
	s_add_u32 s24, s22, 0x4000
	s_addc_u32 s25, s23, 0
	s_cmp_eq_u32 s47, 60
	s_cselect_b32 s27, s11, s25
	s_cselect_b32 s26, s43, s24
	s_cselect_b32 s25, s9, s46
	s_cselect_b32 s24, s44, s45
	v_lshl_add_u64 v[214:215], s[22:23], 0, v[136:137]
	s_add_i32 m0, s19, 0xc000
	ds_read_b128 v[182:185], v150
	ds_read_b128 v[186:189], v150 offset:1024
	ds_read_b128 v[190:193], v150 offset:2048
	ds_read_b128 v[194:197], v150 offset:3072
	ds_read_b128 v[198:201], v150 offset:4096
	ds_read_b128 v[202:205], v150 offset:5120
	ds_read_b128 v[206:209], v150 offset:6144
	ds_read_b128 v[210:213], v150 offset:7168
	global_load_lds_dwordx4 v[214:215], off
	v_lshl_add_u64 v[214:215], s[22:23], 0, v[138:139]
	s_add_i32 m0, s19, 0xe000
	s_nop 0
	global_load_lds_dwordx4 v[214:215], off
	s_waitcnt vmcnt(8)
	s_waitcnt lgkmcnt(0)
	s_barrier
	s_setprio 1
	v_mfma_f32_16x16x32_bf16 v[124:127], v[142:145], v[182:185], v[124:127]
	v_mfma_f32_16x16x32_bf16 v[120:123], v[158:161], v[182:185], v[120:123]
	v_mfma_f32_16x16x32_bf16 v[108:111], v[142:145], v[190:193], v[108:111]
	v_mfma_f32_16x16x32_bf16 v[104:107], v[158:161], v[190:193], v[104:107]
	v_mfma_f32_16x16x32_bf16 v[92:95], v[142:145], v[198:201], v[92:95]
	v_mfma_f32_16x16x32_bf16 v[88:91], v[158:161], v[198:201], v[88:91]
	v_mfma_f32_16x16x32_bf16 v[76:79], v[142:145], v[206:209], v[76:79]
	v_mfma_f32_16x16x32_bf16 v[72:75], v[158:161], v[206:209], v[72:75]
	v_mfma_f32_16x16x32_bf16 v[124:127], v[154:157], v[186:189], v[124:127]
	v_mfma_f32_16x16x32_bf16 v[120:123], v[162:165], v[186:189], v[120:123]
	v_mfma_f32_16x16x32_bf16 v[108:111], v[154:157], v[194:197], v[108:111]
	v_mfma_f32_16x16x32_bf16 v[104:107], v[162:165], v[194:197], v[104:107]
	v_mfma_f32_16x16x32_bf16 v[92:95], v[154:157], v[202:205], v[92:95]
	v_mfma_f32_16x16x32_bf16 v[88:91], v[162:165], v[202:205], v[88:91]
	v_mfma_f32_16x16x32_bf16 v[76:79], v[154:157], v[210:213], v[76:79]
	v_mfma_f32_16x16x32_bf16 v[72:75], v[162:165], v[210:213], v[72:75]
	s_setprio 0
	s_setprio 1
	v_mfma_f32_16x16x32_bf16 v[116:119], v[166:169], v[182:185], v[116:119]
	v_mfma_f32_16x16x32_bf16 v[112:115], v[174:177], v[182:185], v[112:115]
	v_mfma_f32_16x16x32_bf16 v[100:103], v[166:169], v[190:193], v[100:103]
	v_mfma_f32_16x16x32_bf16 v[96:99], v[174:177], v[190:193], v[96:99]
	v_mfma_f32_16x16x32_bf16 v[84:87], v[166:169], v[198:201], v[84:87]
	v_mfma_f32_16x16x32_bf16 v[80:83], v[174:177], v[198:201], v[80:83]
	v_mfma_f32_16x16x32_bf16 v[68:71], v[166:169], v[206:209], v[68:71]
	v_mfma_f32_16x16x32_bf16 v[64:67], v[174:177], v[206:209], v[64:67]
	v_mfma_f32_16x16x32_bf16 v[116:119], v[170:173], v[186:189], v[116:119]
	v_mfma_f32_16x16x32_bf16 v[112:115], v[178:181], v[186:189], v[112:115]
	v_mfma_f32_16x16x32_bf16 v[100:103], v[170:173], v[194:197], v[100:103]
	v_mfma_f32_16x16x32_bf16 v[96:99], v[178:181], v[194:197], v[96:99]
	v_mfma_f32_16x16x32_bf16 v[84:87], v[170:173], v[202:205], v[84:87]
	v_mfma_f32_16x16x32_bf16 v[80:83], v[178:181], v[202:205], v[80:83]
	v_mfma_f32_16x16x32_bf16 v[68:71], v[170:173], v[210:213], v[68:71]
	v_mfma_f32_16x16x32_bf16 v[64:67], v[178:181], v[210:213], v[64:67]
	s_setprio 0
	s_barrier
	s_add_i32 s48, s37, s29
	v_lshl_add_u64 v[214:215], s[24:25], 0, v[130:131]
	s_mov_b32 m0, s48
	ds_read_b128 v[182:185], v150 offset:16384
	ds_read_b128 v[186:189], v150 offset:17408
	ds_read_b128 v[190:193], v150 offset:18432
	ds_read_b128 v[194:197], v150 offset:19456
	ds_read_b128 v[198:201], v150 offset:20480
	ds_read_b128 v[202:205], v150 offset:21504
	ds_read_b128 v[206:209], v150 offset:22528
	ds_read_b128 v[210:213], v150 offset:23552
	global_load_lds_dwordx4 v[214:215], off
	s_add_i32 m0, s48, 0x2000
	s_add_u32 s48, s24, 0x100000
	v_lshl_add_u64 v[216:217], s[24:25], 0, v[134:135]
	s_addc_u32 s49, s25, 0
	s_add_i32 s52, s38, s29
	global_load_lds_dwordx4 v[216:217], off
	v_lshl_add_u64 v[218:219], s[48:49], 0, v[130:131]
	s_mov_b32 m0, s52
	v_lshl_add_u64 v[220:221], s[26:27], 0, v[132:133]
	global_load_lds_dwordx4 v[218:219], off
	v_lshl_add_u64 v[218:219], s[48:49], 0, v[134:135]
	s_add_i32 m0, s52, 0x2000
	s_nop 0
	global_load_lds_dwordx4 v[218:219], off
	v_lshl_add_u64 v[218:219], s[26:27], 0, v[128:129]
	s_mov_b32 m0, s19
	s_nop 0
	global_load_lds_dwordx4 v[218:219], off
	s_mov_b32 m0, s21
	s_nop 0
	global_load_lds_dwordx4 v[220:221], off
	s_waitcnt vmcnt(8)
	s_waitcnt lgkmcnt(0)
	s_barrier
; #define PG8_STAGE(bufoff, gbase, voff) do { _Pragma("unroll") for (int _i = 0; _i < 2; ++_i) \
;         __builtin_amdgcn_global_load_lds((const unsigned*)((const char*)(gbase) + (voff)[_i]), (PG8_LAS unsigned*)(lds + (bufoff) + ldsw + _i * 8192), 16, 0, 0); } while (0)
; #define PG8_LDA(dst, b, h) do { _Pragma("unroll") for (int m = 0; m < 4; ++m) _Pragma("unroll") for (int k = 0; k < 2; ++k) dst[m][k] = *(const PG8_LAS bf16x8*)(lds + PG8_SA(b, h) + aoff + m * 2048 + k * 1024); } while (0)
; #define PG8_LDB(dst, b, h) do { _Pragma("unroll") for (int n = 0; n < 2; ++n) _Pragma("unroll") for (int k = 0; k < 2; ++k) dst[n][k] = *(const PG8_LAS bf16x8*)(lds + PG8_SB(b, h) + boff + n * 2048 + k * 1024); } while (0)
; #define PG8_MMA(ai, bj, At, Bt) do { __builtin_amdgcn_s_setprio(1); _Pragma("unroll") for (int m = 0; m < 4; ++m) _Pragma("unroll") for (int n = 0; n < 2; ++n) _Pragma("unroll") for (int k = 0; k < 2; ++k) \
;         acc[ai][bj][m][n] = __builtin_amdgcn_mfma_f32_16x16x32_bf16(Bt[n][k], At[m][k], acc[ai][bj][m][n], 0, 0, 0); __builtin_amdgcn_s_setprio(0); } while (0)
; #define PG8_WAIT_V(n) asm volatile("s_waitcnt vmcnt(" #n ")" ::: "memory")
; #define PG8_WAIT_L(n) asm volatile("s_waitcnt lgkmcnt(" #n ")" ::: "memory")
; #define PG8_BAR __builtin_amdgcn_s_barrier()
; #define PG8_SCHED __builtin_amdgcn_sched_barrier(0)
; template <class Epi, class Sched, bool ALIGN_EPI = false, bool SP2 = false>
; __device__ __forceinline__ void gemm_phase(PG8_LAS unsigned char* lds, const Gemm g, const Sched& S, const Epi& E) {
;     ...
;             PG8_WAIT_V(8); PG8_WAIT_L(0); PG8_BAR; PG8_MMA(1, 0, At, B0); PG8_MMA(1, 1, At, B1); PG8_BAR; PG8_SCHED;
;             PG8_LDB(B0, 1, 0); PG8_LDB(B1, 1, 1); PG8_SCHED; PG8_LDA(At, 1, 0); PG8_STAGE(PG8_SA(0, 1), a2 + hstep, voffA);
;             PG8_WAIT_V(8); PG8_WAIT_L(0); PG8_BAR; PG8_MMA(0, 0, At, B0); PG8_MMA(0, 1, At, B1); PG8_BAR; PG8_SCHED;
	s_setprio 1
	v_mfma_f32_16x16x32_bf16 v[60:63], v[142:145], v[182:185], v[60:63]
	v_mfma_f32_16x16x32_bf16 v[56:59], v[158:161], v[182:185], v[56:59]
	v_mfma_f32_16x16x32_bf16 v[44:47], v[142:145], v[190:193], v[44:47]
	v_mfma_f32_16x16x32_bf16 v[40:43], v[158:161], v[190:193], v[40:43]
	v_mfma_f32_16x16x32_bf16 v[28:31], v[142:145], v[198:201], v[28:31]
	v_mfma_f32_16x16x32_bf16 v[24:27], v[158:161], v[198:201], v[24:27]
	v_mfma_f32_16x16x32_bf16 v[12:15], v[142:145], v[206:209], v[12:15]
	v_mfma_f32_16x16x32_bf16 v[8:11], v[158:161], v[206:209], v[8:11]
	v_mfma_f32_16x16x32_bf16 v[60:63], v[154:157], v[186:189], v[60:63]
	v_mfma_f32_16x16x32_bf16 v[56:59], v[162:165], v[186:189], v[56:59]
	v_mfma_f32_16x16x32_bf16 v[44:47], v[154:157], v[194:197], v[44:47]
	v_mfma_f32_16x16x32_bf16 v[40:43], v[162:165], v[194:197], v[40:43]
	v_mfma_f32_16x16x32_bf16 v[28:31], v[154:157], v[202:205], v[28:31]
	v_mfma_f32_16x16x32_bf16 v[24:27], v[162:165], v[202:205], v[24:27]
	v_mfma_f32_16x16x32_bf16 v[12:15], v[154:157], v[210:213], v[12:15]
	v_mfma_f32_16x16x32_bf16 v[8:11], v[162:165], v[210:213], v[8:11]
	s_setprio 0
	s_setprio 1
	v_mfma_f32_16x16x32_bf16 v[52:55], v[166:169], v[182:185], v[52:55]
	v_mfma_f32_16x16x32_bf16 v[48:51], v[174:177], v[182:185], v[48:51]
	v_mfma_f32_16x16x32_bf16 v[36:39], v[166:169], v[190:193], v[36:39]
	v_mfma_f32_16x16x32_bf16 v[32:35], v[174:177], v[190:193], v[32:35]
	v_mfma_f32_16x16x32_bf16 v[20:23], v[166:169], v[198:201], v[20:23]
	v_mfma_f32_16x16x32_bf16 v[16:19], v[174:177], v[198:201], v[16:19]
	v_mfma_f32_16x16x32_bf16 v[4:7], v[166:169], v[206:209], v[4:7]
	v_mfma_f32_16x16x32_bf16 v[0:3], v[174:177], v[206:209], v[0:3]
	v_mfma_f32_16x16x32_bf16 v[52:55], v[170:173], v[186:189], v[52:55]
	v_mfma_f32_16x16x32_bf16 v[48:51], v[178:181], v[186:189], v[48:51]
	v_mfma_f32_16x16x32_bf16 v[36:39], v[170:173], v[194:197], v[36:39]
	v_mfma_f32_16x16x32_bf16 v[32:35], v[178:181], v[194:197], v[32:35]
	v_mfma_f32_16x16x32_bf16 v[20:23], v[170:173], v[202:205], v[20:23]
	v_mfma_f32_16x16x32_bf16 v[16:19], v[178:181], v[202:205], v[16:19]
	v_mfma_f32_16x16x32_bf16 v[4:7], v[170:173], v[210:213], v[4:7]
	v_mfma_f32_16x16x32_bf16 v[0:3], v[178:181], v[210:213], v[0:3]
	s_setprio 0
	s_barrier
	ds_read_b128 v[142:145], v151
	ds_read_b128 v[154:157], v151 offset:1024
	ds_read_b128 v[158:161], v151 offset:2048
	ds_read_b128 v[162:165], v151 offset:3072
	ds_read_b128 v[166:169], v152
	ds_read_b128 v[170:173], v152 offset:1024
	ds_read_b128 v[174:177], v152 offset:2048
	ds_read_b128 v[178:181], v152 offset:3072
	s_add_u32 s26, s26, 0x4000
	s_addc_u32 s27, s27, 0
	s_mov_b32 m0, s31
	v_lshl_add_u64 v[222:223], s[26:27], 0, v[128:129]
	ds_read_b128 v[182:185], v150 offset:32768
	ds_read_b128 v[186:189], v150 offset:33792
	ds_read_b128 v[190:193], v150 offset:34816
	ds_read_b128 v[194:197], v150 offset:35840
	ds_read_b128 v[198:201], v150 offset:36864
	ds_read_b128 v[202:205], v150 offset:37888
	ds_read_b128 v[206:209], v150 offset:38912
	ds_read_b128 v[210:213], v150 offset:39936
	global_load_lds_dwordx4 v[222:223], off
	v_lshl_add_u64 v[222:223], s[26:27], 0, v[132:133]
	s_mov_b32 m0, s33
	s_nop 0
	global_load_lds_dwordx4 v[222:223], off
	s_waitcnt vmcnt(8)
	s_waitcnt lgkmcnt(0)
	s_barrier
	s_setprio 1
	v_mfma_f32_16x16x32_bf16 v[124:127], v[142:145], v[182:185], v[124:127]
	v_mfma_f32_16x16x32_bf16 v[120:123], v[158:161], v[182:185], v[120:123]
	v_mfma_f32_16x16x32_bf16 v[108:111], v[142:145], v[190:193], v[108:111]
	v_mfma_f32_16x16x32_bf16 v[104:107], v[158:161], v[190:193], v[104:107]
	v_mfma_f32_16x16x32_bf16 v[92:95], v[142:145], v[198:201], v[92:95]
	v_mfma_f32_16x16x32_bf16 v[88:91], v[158:161], v[198:201], v[88:91]
	v_mfma_f32_16x16x32_bf16 v[76:79], v[142:145], v[206:209], v[76:79]
	v_mfma_f32_16x16x32_bf16 v[72:75], v[158:161], v[206:209], v[72:75]
	v_mfma_f32_16x16x32_bf16 v[124:127], v[154:157], v[186:189], v[124:127]
	v_mfma_f32_16x16x32_bf16 v[120:123], v[162:165], v[186:189], v[120:123]
	v_mfma_f32_16x16x32_bf16 v[108:111], v[154:157], v[194:197], v[108:111]
	v_mfma_f32_16x16x32_bf16 v[104:107], v[162:165], v[194:197], v[104:107]
	v_mfma_f32_16x16x32_bf16 v[92:95], v[154:157], v[202:205], v[92:95]
	v_mfma_f32_16x16x32_bf16 v[88:91], v[162:165], v[202:205], v[88:91]
	v_mfma_f32_16x16x32_bf16 v[76:79], v[154:157], v[210:213], v[76:79]
	v_mfma_f32_16x16x32_bf16 v[72:75], v[162:165], v[210:213], v[72:75]
	s_setprio 0
	s_setprio 1
	v_mfma_f32_16x16x32_bf16 v[116:119], v[166:169], v[182:185], v[116:119]
	v_mfma_f32_16x16x32_bf16 v[112:115], v[174:177], v[182:185], v[112:115]
	v_mfma_f32_16x16x32_bf16 v[100:103], v[166:169], v[190:193], v[100:103]
	v_mfma_f32_16x16x32_bf16 v[96:99], v[174:177], v[190:193], v[96:99]
	v_mfma_f32_16x16x32_bf16 v[84:87], v[166:169], v[198:201], v[84:87]
	v_mfma_f32_16x16x32_bf16 v[80:83], v[174:177], v[198:201], v[80:83]
	v_mfma_f32_16x16x32_bf16 v[68:71], v[166:169], v[206:209], v[68:71]
	v_mfma_f32_16x16x32_bf16 v[64:67], v[174:177], v[206:209], v[64:67]
	v_mfma_f32_16x16x32_bf16 v[116:119], v[170:173], v[186:189], v[116:119]
	v_mfma_f32_16x16x32_bf16 v[112:115], v[178:181], v[186:189], v[112:115]
	v_mfma_f32_16x16x32_bf16 v[100:103], v[170:173], v[194:197], v[100:103]
	v_mfma_f32_16x16x32_bf16 v[96:99], v[178:181], v[194:197], v[96:99]
	v_mfma_f32_16x16x32_bf16 v[84:87], v[170:173], v[202:205], v[84:87]
	v_mfma_f32_16x16x32_bf16 v[80:83], v[178:181], v[202:205], v[80:83]
	v_mfma_f32_16x16x32_bf16 v[68:71], v[170:173], v[210:213], v[68:71]
	v_mfma_f32_16x16x32_bf16 v[64:67], v[178:181], v[210:213], v[64:67]
	s_setprio 0
	s_barrier
; #define PG8_STAGE(bufoff, gbase, voff) do { _Pragma("unroll") for (int _i = 0; _i < 2; ++_i) \
;         __builtin_amdgcn_global_load_lds((const unsigned*)((const char*)(gbase) + (voff)[_i]), (PG8_LAS unsigned*)(lds + (bufoff) + ldsw + _i * 8192), 16, 0, 0); } while (0)
; #define PG8_LDA(dst, b, h) do { _Pragma("unroll") for (int m = 0; m < 4; ++m) _Pragma("unroll") for (int k = 0; k < 2; ++k) dst[m][k] = *(const PG8_LAS bf16x8*)(lds + PG8_SA(b, h) + aoff + m * 2048 + k * 1024); } while (0)
; #define PG8_MMA(ai, bj, At, Bt) do { __builtin_amdgcn_s_setprio(1); _Pragma("unroll") for (int m = 0; m < 4; ++m) _Pragma("unroll") for (int n = 0; n < 2; ++n) _Pragma("unroll") for (int k = 0; k < 2; ++k) \
;         acc[ai][bj][m][n] = __builtin_amdgcn_mfma_f32_16x16x32_bf16(Bt[n][k], At[m][k], acc[ai][bj][m][n], 0, 0, 0); __builtin_amdgcn_s_setprio(0); } while (0)
; #define PG8_WAIT_V(n) asm volatile("s_waitcnt vmcnt(" #n ")" ::: "memory")
; #define PG8_WAIT_L(n) asm volatile("s_waitcnt lgkmcnt(" #n ")" ::: "memory")
; #define PG8_BAR __builtin_amdgcn_s_barrier()
; #define PG8_SCHED __builtin_amdgcn_sched_barrier(0)
; template <class Epi, class Sched, bool ALIGN_EPI = false, bool SP2 = false>
; __device__ __forceinline__ void gemm_phase(PG8_LAS unsigned char* lds, const Gemm g, const Sched& S, const Epi& E) {
;     ...
;             PG8_LDA(At, 1, 1); PG8_STAGE(PG8_SB(1, 0), b3, voffB); PG8_STAGE(PG8_SB(1, 1), b3 + hstep, voffB); PG8_STAGE(PG8_SA(1, 0), a3, voffA);
;             PG8_WAIT_V(8); PG8_WAIT_L(0); PG8_BAR; PG8_MMA(1, 0, At, B0); PG8_MMA(1, 1, At, B1); PG8_BAR; PG8_SCHED;
;     ...
;         if constexpr (ALIGN_EPI) { if (wr == 0) PG8_BAR; }
	s_add_i32 s26, s39, s29
	v_lshl_add_u64 v[214:215], v[214:215], 0, s[4:5]
	s_mov_b32 m0, s26
	ds_read_b128 v[182:185], v150 offset:49152
	ds_read_b128 v[186:189], v150 offset:50176
	ds_read_b128 v[190:193], v150 offset:51200
	ds_read_b128 v[194:197], v150 offset:52224
	ds_read_b128 v[198:201], v150 offset:53248
	ds_read_b128 v[202:205], v150 offset:54272
	ds_read_b128 v[206:209], v150 offset:55296
	ds_read_b128 v[210:213], v150 offset:56320
	global_load_lds_dwordx4 v[214:215], off
	s_add_i32 m0, s26, 0x2000
	s_add_u32 s24, s24, 0x100080
	v_lshl_add_u64 v[214:215], v[216:217], 0, s[4:5]
	s_addc_u32 s25, s25, 0
	s_add_i32 s26, s40, s29
	global_load_lds_dwordx4 v[214:215], off
	v_lshl_add_u64 v[214:215], s[24:25], 0, v[130:131]
	s_mov_b32 m0, s26
	s_nop 0
	global_load_lds_dwordx4 v[214:215], off
	v_lshl_add_u64 v[214:215], s[24:25], 0, v[134:135]
	s_add_i32 m0, s26, 0x2000
	s_nop 0
	global_load_lds_dwordx4 v[214:215], off
	v_lshl_add_u64 v[214:215], v[218:219], 0, s[70:71]
	s_mov_b32 m0, s34
	s_nop 0
	global_load_lds_dwordx4 v[214:215], off
	v_lshl_add_u64 v[214:215], v[220:221], 0, s[70:71]
	s_mov_b32 m0, s35
	s_nop 0
	global_load_lds_dwordx4 v[214:215], off
	s_waitcnt vmcnt(8)
	s_waitcnt lgkmcnt(0)
	s_barrier
	s_setprio 1
	v_mfma_f32_16x16x32_bf16 v[60:63], v[142:145], v[182:185], v[60:63]
	v_mfma_f32_16x16x32_bf16 v[56:59], v[158:161], v[182:185], v[56:59]
	v_mfma_f32_16x16x32_bf16 v[44:47], v[142:145], v[190:193], v[44:47]
	v_mfma_f32_16x16x32_bf16 v[40:43], v[158:161], v[190:193], v[40:43]
	v_mfma_f32_16x16x32_bf16 v[28:31], v[142:145], v[198:201], v[28:31]
	v_mfma_f32_16x16x32_bf16 v[24:27], v[158:161], v[198:201], v[24:27]
	v_mfma_f32_16x16x32_bf16 v[12:15], v[142:145], v[206:209], v[12:15]
	v_mfma_f32_16x16x32_bf16 v[8:11], v[158:161], v[206:209], v[8:11]
	v_mfma_f32_16x16x32_bf16 v[60:63], v[154:157], v[186:189], v[60:63]
	v_mfma_f32_16x16x32_bf16 v[56:59], v[162:165], v[186:189], v[56:59]
	v_mfma_f32_16x16x32_bf16 v[44:47], v[154:157], v[194:197], v[44:47]
	v_mfma_f32_16x16x32_bf16 v[40:43], v[162:165], v[194:197], v[40:43]
	v_mfma_f32_16x16x32_bf16 v[28:31], v[154:157], v[202:205], v[28:31]
	v_mfma_f32_16x16x32_bf16 v[24:27], v[162:165], v[202:205], v[24:27]
	v_mfma_f32_16x16x32_bf16 v[12:15], v[154:157], v[210:213], v[12:15]
	v_mfma_f32_16x16x32_bf16 v[8:11], v[162:165], v[210:213], v[8:11]
	s_setprio 0
	s_setprio 1
	v_mfma_f32_16x16x32_bf16 v[52:55], v[166:169], v[182:185], v[52:55]
	v_mfma_f32_16x16x32_bf16 v[48:51], v[174:177], v[182:185], v[48:51]
	v_mfma_f32_16x16x32_bf16 v[36:39], v[166:169], v[190:193], v[36:39]
	v_mfma_f32_16x16x32_bf16 v[32:35], v[174:177], v[190:193], v[32:35]
	v_mfma_f32_16x16x32_bf16 v[20:23], v[166:169], v[198:201], v[20:23]
	v_mfma_f32_16x16x32_bf16 v[16:19], v[174:177], v[198:201], v[16:19]
	v_mfma_f32_16x16x32_bf16 v[4:7], v[166:169], v[206:209], v[4:7]
	v_mfma_f32_16x16x32_bf16 v[0:3], v[174:177], v[206:209], v[0:3]
	v_mfma_f32_16x16x32_bf16 v[52:55], v[170:173], v[186:189], v[52:55]
	v_mfma_f32_16x16x32_bf16 v[48:51], v[178:181], v[186:189], v[48:51]
	v_mfma_f32_16x16x32_bf16 v[36:39], v[170:173], v[194:197], v[36:39]
	v_mfma_f32_16x16x32_bf16 v[32:35], v[178:181], v[194:197], v[32:35]
	v_mfma_f32_16x16x32_bf16 v[20:23], v[170:173], v[202:205], v[20:23]
	v_mfma_f32_16x16x32_bf16 v[16:19], v[178:181], v[202:205], v[16:19]
	v_mfma_f32_16x16x32_bf16 v[4:7], v[170:173], v[210:213], v[4:7]
	v_mfma_f32_16x16x32_bf16 v[0:3], v[178:181], v[210:213], v[0:3]
	s_setprio 0
	s_barrier
	s_add_i32 s47, s47, 2
	s_add_u32 s22, s22, 0x10000
	s_addc_u32 s23, s23, 0
	s_add_u32 s45, s45, 0x100
	s_addc_u32 s46, s46, 0
	s_cmp_gt_u32 s47, 61
	s_cbranch_scc0 .LBB0_1498
	s_and_b64 vcc, exec, s[6:7]
	s_cbranch_vccz .LBB0_1501
	s_barrier
